# q_tile/kv_tile GEMMs: the two 256-thread halves staggered by half an iteration via one extra mid-iteration barrier (one half stages LDS while the other reads+MFMAs)
# speedup vs baseline: 1.0176x; 1.0050x over previous
; #define MFMA(a, b, c) __builtin_amdgcn_mfma_f32_32x32x16_bf16((a), (b), (c), 0, 0, 0)
; template <int BM, int BN, int BK, int WAVES_M, int WAVES_N, int UNSWAP_FROM>
; DI void gemm_mainloop(const int tid, const bf16_t* __restrict__ A, int lda, const bf16_t* __restrict__ Bt, int ldb, int K, unsigned char* smem,
;                       f32x16 (&acc)[BM / WAVES_M / 32][BN / WAVES_N / 32]) {
;     ...
;     const int nk = K / BK;
;     ...
;     G_LOAD(0); G_STORE(0); __syncthreads();
;     for (int kt = 0; kt < nk; ++kt) {
;         const int buf = kt & 1;
;         if (kt + 1 < nk) G_LOAD(kt + 1);
;         const unsigned char* sa_ = smem + buf * STAGE; const unsigned char* sb_ = sa_ + A_ST;
; #pragma unroll
;         for (int ks = 0; ks < BK / 16; ++ks) {
;             bf16x8 af[WM], bfr[WN];
; #pragma unroll
;             for (int i = 0; i < WM; ++i) af[i] = *(const bf16x8*)(sa_ + (((wm * WM + i) * 32 + r) * LS + ks * 16 + h * 8) * 2);
; #pragma unroll
;             for (int j = 0; j < WN; ++j) bfr[j] = *(const bf16x8*)(sb_ + (((wn * WN + j) * 32 + r) * LS + ks * 16 + h * 8) * 2);
; #pragma unroll
;             for (int i = 0; i < WM; ++i)
; #pragma unroll
;                 for (int j = 0; j < WN; ++j) {
;                     if (j < UNSWAP_FROM) acc[i][j] = MFMA(bfr[j], af[i], acc[i][j]);
;                     else acc[i][j] = MFMA(af[i], bfr[j], acc[i][j]);
;                 }
;         }
;         if (kt + 1 < nk) G_STORE(buf ^ 1);
;         __syncthreads();
; DI void phase2(const Params& p, unsigned char* smem) {
;     ...
;         else if (it < 6144) { const int r = it - 4096; q_tile(p, r >> 3, r & 7, smem); }
;         else { const int r = it - 6144; kv_tile(p, r >> 3, r & 7, smem); }
.LBB0_158:
	s_cmpk_gt_i32 s51, 0xfff
	s_mov_b64 s[4:5], -1
	s_cbranch_scc0 .LBB0_164
	s_and_b32 s15, s51, 7
	s_cmpk_gt_u32 s51, 0x17ff
	s_cbranch_scc0 .LBB0_161
	v_mov_b32_e32 v79, v227
	s_add_i32 s4, s51, 0xffffe800
	s_lshr_b32 s4, s4, 3
	v_ashrrev_i32_e32 v0, 1, v79
	v_and_b32_e32 v0, 0xffffffe0, v0
	v_lshl_add_u32 v64, s4, 7, v0
	v_ashrrev_i32_e32 v0, 31, v79
	s_mul_i32 s44, s4, 0x5c000
	v_lshrrev_b32_e32 v0, 30, v0
	s_lshl_b64 s[4:5], s[44:45], 1
	v_add_u32_e32 v0, v79, v0
	s_add_u32 s4, s8, s4
	v_ashrrev_i32_e32 v16, 2, v0
	v_and_b32_e32 v0, -4, v0
	s_addc_u32 s5, s9, s5
	s_lshl_b32 s44, s15, 17
	v_readlane_b32 s74, v244, 25
	v_sub_u32_e32 v20, v79, v0
	s_add_u32 s74, s74, s44
	v_readlane_b32 s44, v244, 26
	v_lshlrev_b32_e32 v2, 3, v20
	v_add_u32_e32 v6, 0x100, v79
	s_addc_u32 s75, s44, 0
	v_mov_b64_e32 v[4:5], s[4:5]
	s_movk_i32 s44, 0x1700
	v_ashrrev_i32_e32 v3, 31, v2
	v_ashrrev_i32_e32 v7, 31, v6
	v_mad_i64_i32 v[0:1], s[4:5], v16, s44, v[4:5]
	v_lshlrev_b64 v[72:73], 1, v[2:3]
	v_lshrrev_b32_e32 v7, 30, v7
	v_lshl_add_u64 v[66:67], v[0:1], 0, v[72:73]
	v_add_u32_e32 v7, v6, v7
	global_load_dwordx4 v[0:3], v[66:67], off offset:1024
	v_ashrrev_i32_e32 v18, 2, v7
	v_and_b32_e32 v7, -4, v7
	v_sub_u32_e32 v21, v6, v7
	v_lshlrev_b32_e32 v6, 3, v21
	s_add_u32 s76, s74, 0x10000
	v_ashrrev_i32_e32 v17, 31, v16
	v_ashrrev_i32_e32 v7, 31, v6
	s_addc_u32 s77, s75, 0
	v_ashrrev_i32_e32 v19, 31, v18
	v_mad_i64_i32 v[4:5], s[4:5], v18, s44, v[4:5]
	v_lshlrev_b64 v[70:71], 1, v[6:7]
	v_lshlrev_b64 v[76:77], 9, v[16:17]
	v_lshl_add_u64 v[68:69], v[4:5], 0, v[70:71]
	v_lshl_add_u64 v[8:9], s[76:77], 0, v[76:77]
	v_lshlrev_b64 v[74:75], 9, v[18:19]
	global_load_dwordx4 v[4:7], v[68:69], off offset:1024
	v_lshl_add_u64 v[8:9], v[8:9], 0, v[72:73]
	v_lshl_add_u64 v[12:13], s[76:77], 0, v[74:75]
	global_load_dwordx4 v[8:11], v[8:9], off
	v_lshl_add_u64 v[12:13], v[12:13], 0, v[70:71]
	global_load_dwordx4 v[12:15], v[12:13], off
	s_movk_i32 s4, 0x50
	v_lshlrev_b32_e32 v17, 4, v20
	v_mul_lo_u32 v16, v16, s4
	v_add3_u32 v93, v17, v16, s10
	v_and_b32_e32 v92, 31, v79
	s_mov_b32 s5, 0xfffffe0
	v_ashrrev_i32_e32 v65, 10, v64
	v_readlane_b32 s76, v244, 27
	v_and_or_b32 v78, v65, -8, s15
	v_ashrrev_i32_e32 v65, 31, v64
	v_readlane_b32 s77, v244, 28
	v_and_b32_e32 v97, 0x1fe0, v64
	s_waitcnt vmcnt(3)
	ds_write_b128 v93, v[0:3]
	v_lshlrev_b32_e32 v0, 4, v21
	v_mul_lo_u32 v1, v18, s4
	v_add3_u32 v94, v0, v1, s10
	v_lshrrev_b32_e32 v0, 1, v79
	v_and_or_b32 v1, v0, s5, v92
	v_mul_lo_u32 v3, v1, s4
	s_add_u32 s4, s74, 0x10040
	s_addc_u32 s5, s75, 0
	v_and_b32_e32 v2, 16, v0
	v_lshl_add_u64 v[0:1], s[4:5], 0, v[76:77]
	s_waitcnt vmcnt(2)
	ds_write_b128 v94, v[4:7]
	s_waitcnt vmcnt(1)
	ds_write_b128 v93, v[8:11] offset:10240
	s_waitcnt vmcnt(0)
	ds_write_b128 v94, v[12:15] offset:10240
	s_waitcnt lgkmcnt(0)
	s_barrier
	s_cmp_eq_u32 s10, 0
	s_cbranch_scc1 .Lkv_stg_beg0
	s_barrier
.Lkv_stg_beg0:
	global_load_dwordx4 v[80:83], v[66:67], off offset:1088
	global_load_dwordx4 v[84:87], v[68:69], off offset:1088
	v_lshl_add_u64 v[0:1], v[0:1], 0, v[72:73]
	global_load_dwordx4 v[88:91], v[0:1], off
	v_lshl_add_u64 v[0:1], s[4:5], 0, v[74:75]
	v_lshl_add_u64 v[0:1], v[0:1], 0, v[70:71]
	global_load_dwordx4 v[98:101], v[0:1], off
	v_mul_u32_u24_e32 v4, 0x50, v92
	s_add_u32 s4, s74, 0x10080
	v_add3_u32 v95, v2, v4, s10
	s_addc_u32 s5, s75, 0
	v_add3_u32 v96, v3, v2, s10
	ds_read_b128 v[0:3], v95 offset:12800
	ds_read_b128 v[4:7], v95 offset:15360
	ds_read_b128 v[8:11], v95 offset:17920
	ds_read_b128 v[12:15], v96
	ds_read_b128 v[102:105], v96 offset:32
	ds_read_b128 v[16:19], v95 offset:10240
	ds_read_b128 v[106:109], v95 offset:10272
	ds_read_b128 v[110:113], v95 offset:12832
	ds_read_b128 v[120:123], v95 offset:15392
	ds_read_b128 v[124:127], v95 offset:17952
	s_waitcnt lgkmcnt(4)
	v_mfma_f32_32x32x16_bf16 v[48:63], v[12:15], v[16:19], 0
	s_barrier
	s_waitcnt vmcnt(3)
	ds_write_b128 v93, v[80:83] offset:20480
	s_waitcnt vmcnt(2)
	ds_write_b128 v94, v[84:87] offset:20480
	s_waitcnt vmcnt(1)
	ds_write_b128 v93, v[88:91] offset:30720
	s_waitcnt vmcnt(0)
	ds_write_b128 v94, v[98:101] offset:30720
	s_waitcnt lgkmcnt(0)
	s_barrier
	global_load_dwordx4 v[80:83], v[66:67], off offset:1152
	global_load_dwordx4 v[84:87], v[68:69], off offset:1152
	v_lshl_add_u64 v[88:89], s[4:5], 0, v[76:77]
	v_lshl_add_u64 v[88:89], v[88:89], 0, v[72:73]
	v_lshl_add_u64 v[98:99], s[4:5], 0, v[74:75]
	global_load_dwordx4 v[88:91], v[88:89], off
	v_lshl_add_u64 v[98:99], v[98:99], 0, v[70:71]
	global_load_dwordx4 v[98:101], v[98:99], off
	v_mfma_f32_32x32x16_bf16 v[32:47], v[12:15], v[0:3], 0
	s_add_u32 s4, s74, 0x100c0
	s_addc_u32 s5, s75, 0
	v_mfma_f32_32x32x16_bf16 v[16:31], v[12:15], v[4:7], 0
	v_mfma_f32_32x32x16_bf16 v[0:15], v[12:15], v[8:11], 0
	v_mfma_f32_32x32x16_bf16 v[32:47], v[102:105], v[110:113], v[32:47]
	v_mfma_f32_32x32x16_bf16 v[16:31], v[102:105], v[120:123], v[16:31]
	v_mfma_f32_32x32x16_bf16 v[0:15], v[102:105], v[124:127], v[0:15]
	v_mfma_f32_32x32x16_bf16 v[48:63], v[102:105], v[106:109], v[48:63]
	ds_read_b128 v[102:105], v95 offset:33280
	ds_read_b128 v[106:109], v95 offset:35840
	ds_read_b128 v[110:113], v95 offset:38400
	ds_read_b128 v[120:123], v96 offset:20480
	ds_read_b128 v[124:127], v96 offset:20512
	ds_read_b128 v[128:131], v95 offset:30720
	ds_read_b128 v[132:135], v95 offset:30752
	s_waitcnt lgkmcnt(3)
	v_mfma_f32_32x32x16_bf16 v[32:47], v[120:123], v[102:105], v[32:47]
	v_mfma_f32_32x32x16_bf16 v[16:31], v[120:123], v[106:109], v[16:31]
	v_mfma_f32_32x32x16_bf16 v[0:15], v[120:123], v[110:113], v[0:15]
	ds_read_b128 v[102:105], v95 offset:33312
	ds_read_b128 v[106:109], v95 offset:35872
	ds_read_b128 v[110:113], v95 offset:38432
	s_barrier
; #define MFMA(a, b, c) __builtin_amdgcn_mfma_f32_32x32x16_bf16((a), (b), (c), 0, 0, 0)
; template <int BM, int BN, int BK, int WAVES_M, int WAVES_N, int UNSWAP_FROM>
; DI void gemm_mainloop(const int tid, const bf16_t* __restrict__ A, int lda, const bf16_t* __restrict__ Bt, int ldb, int K, unsigned char* smem,
;                       f32x16 (&acc)[BM / WAVES_M / 32][BN / WAVES_N / 32]) {
;     ...
;     for (int kt = 0; kt < nk; ++kt) {
;         const int buf = kt & 1;
;         if (kt + 1 < nk) G_LOAD(kt + 1);
;         const unsigned char* sa_ = smem + buf * STAGE; const unsigned char* sb_ = sa_ + A_ST;
; #pragma unroll
;         for (int ks = 0; ks < BK / 16; ++ks) {
;             bf16x8 af[WM], bfr[WN];
; #pragma unroll
;             for (int i = 0; i < WM; ++i) af[i] = *(const bf16x8*)(sa_ + (((wm * WM + i) * 32 + r) * LS + ks * 16 + h * 8) * 2);
; #pragma unroll
;             for (int j = 0; j < WN; ++j) bfr[j] = *(const bf16x8*)(sb_ + (((wn * WN + j) * 32 + r) * LS + ks * 16 + h * 8) * 2);
; #pragma unroll
;             for (int i = 0; i < WM; ++i)
; #pragma unroll
;                 for (int j = 0; j < WN; ++j) {
;                     if (j < UNSWAP_FROM) acc[i][j] = MFMA(bfr[j], af[i], acc[i][j]);
;                     else acc[i][j] = MFMA(af[i], bfr[j], acc[i][j]);
;                 }
;         }
;         if (kt + 1 < nk) G_STORE(buf ^ 1);
;         __syncthreads();
	s_waitcnt vmcnt(3)
	ds_write_b128 v93, v[80:83]
	s_waitcnt vmcnt(2)
	ds_write_b128 v94, v[84:87]
	s_waitcnt vmcnt(1)
	ds_write_b128 v93, v[88:91] offset:10240
	s_waitcnt vmcnt(0)
	ds_write_b128 v94, v[98:101] offset:10240
	s_waitcnt lgkmcnt(0)
	s_barrier
	global_load_dwordx4 v[80:83], v[66:67], off offset:1216
	global_load_dwordx4 v[84:87], v[68:69], off offset:1216
	v_lshl_add_u64 v[88:89], s[4:5], 0, v[76:77]
	v_lshl_add_u64 v[88:89], v[88:89], 0, v[72:73]
	v_lshl_add_u64 v[98:99], s[4:5], 0, v[74:75]
	global_load_dwordx4 v[88:91], v[88:89], off
	v_lshl_add_u64 v[98:99], v[98:99], 0, v[70:71]
	global_load_dwordx4 v[98:101], v[98:99], off
	v_mfma_f32_32x32x16_bf16 v[48:63], v[120:123], v[128:131], v[48:63]
	s_add_u32 s4, s74, 0x10100
	s_addc_u32 s5, s75, 0
	v_mfma_f32_32x32x16_bf16 v[32:47], v[124:127], v[102:105], v[32:47]
	v_mfma_f32_32x32x16_bf16 v[16:31], v[124:127], v[106:109], v[16:31]
	v_mfma_f32_32x32x16_bf16 v[0:15], v[124:127], v[110:113], v[0:15]
	v_mfma_f32_32x32x16_bf16 v[48:63], v[124:127], v[132:135], v[48:63]
	ds_read_b128 v[102:105], v95 offset:12800
	ds_read_b128 v[106:109], v95 offset:15360
	ds_read_b128 v[110:113], v95 offset:17920
	ds_read_b128 v[120:123], v96
	ds_read_b128 v[124:127], v96 offset:32
	ds_read_b128 v[128:131], v95 offset:10240
	ds_read_b128 v[132:135], v95 offset:10272
	s_waitcnt lgkmcnt(3)
	v_mfma_f32_32x32x16_bf16 v[32:47], v[120:123], v[102:105], v[32:47]
	v_mfma_f32_32x32x16_bf16 v[16:31], v[120:123], v[106:109], v[16:31]
	v_mfma_f32_32x32x16_bf16 v[0:15], v[120:123], v[110:113], v[0:15]
	ds_read_b128 v[102:105], v95 offset:12832
	ds_read_b128 v[106:109], v95 offset:15392
	ds_read_b128 v[110:113], v95 offset:17952
	s_barrier
	s_waitcnt vmcnt(3)
	ds_write_b128 v93, v[80:83] offset:20480
	s_waitcnt vmcnt(2)
	ds_write_b128 v94, v[84:87] offset:20480
	s_waitcnt vmcnt(1)
	ds_write_b128 v93, v[88:91] offset:30720
	s_waitcnt vmcnt(0)
	ds_write_b128 v94, v[98:101] offset:30720
	s_waitcnt lgkmcnt(0)
	s_barrier
	global_load_dwordx4 v[80:83], v[66:67], off offset:1280
	global_load_dwordx4 v[84:87], v[68:69], off offset:1280
	v_lshl_add_u64 v[88:89], s[4:5], 0, v[76:77]
	v_lshl_add_u64 v[88:89], v[88:89], 0, v[72:73]
	v_lshl_add_u64 v[98:99], s[4:5], 0, v[74:75]
	global_load_dwordx4 v[88:91], v[88:89], off
	v_lshl_add_u64 v[98:99], v[98:99], 0, v[70:71]
	global_load_dwordx4 v[98:101], v[98:99], off
	v_mfma_f32_32x32x16_bf16 v[48:63], v[120:123], v[128:131], v[48:63]
	s_add_u32 s4, s74, 0x10140
	s_addc_u32 s5, s75, 0
	v_mfma_f32_32x32x16_bf16 v[32:47], v[124:127], v[102:105], v[32:47]
	v_mfma_f32_32x32x16_bf16 v[16:31], v[124:127], v[106:109], v[16:31]
	v_mfma_f32_32x32x16_bf16 v[0:15], v[124:127], v[110:113], v[0:15]
	v_mfma_f32_32x32x16_bf16 v[48:63], v[124:127], v[132:135], v[48:63]
	ds_read_b128 v[102:105], v95 offset:33280
	ds_read_b128 v[106:109], v95 offset:35840
	ds_read_b128 v[110:113], v95 offset:38400
	ds_read_b128 v[120:123], v96 offset:20480
	ds_read_b128 v[124:127], v96 offset:20512
	ds_read_b128 v[128:131], v95 offset:30720
	ds_read_b128 v[132:135], v95 offset:30752
	s_waitcnt lgkmcnt(3)
	v_mfma_f32_32x32x16_bf16 v[32:47], v[120:123], v[102:105], v[32:47]
	v_mfma_f32_32x32x16_bf16 v[16:31], v[120:123], v[106:109], v[16:31]
	v_mfma_f32_32x32x16_bf16 v[0:15], v[120:123], v[110:113], v[0:15]
	ds_read_b128 v[102:105], v95 offset:33312
	ds_read_b128 v[106:109], v95 offset:35872
	ds_read_b128 v[110:113], v95 offset:38432
	s_barrier
	s_waitcnt vmcnt(3)
	ds_write_b128 v93, v[80:83]
	s_waitcnt vmcnt(2)
	ds_write_b128 v94, v[84:87]
	s_waitcnt vmcnt(1)
	ds_write_b128 v93, v[88:91] offset:10240
	s_waitcnt vmcnt(0)
	ds_write_b128 v94, v[98:101] offset:10240
	s_waitcnt lgkmcnt(0)
	s_barrier
	global_load_dwordx4 v[80:83], v[66:67], off offset:1344
	global_load_dwordx4 v[84:87], v[68:69], off offset:1344
	v_lshl_add_u64 v[88:89], s[4:5], 0, v[76:77]
	v_lshl_add_u64 v[88:89], v[88:89], 0, v[72:73]
	v_lshl_add_u64 v[98:99], s[4:5], 0, v[74:75]
	global_load_dwordx4 v[88:91], v[88:89], off
	v_lshl_add_u64 v[98:99], v[98:99], 0, v[70:71]
	global_load_dwordx4 v[98:101], v[98:99], off
	v_mfma_f32_32x32x16_bf16 v[48:63], v[120:123], v[128:131], v[48:63]
	s_add_u32 s4, s74, 0x10180
	s_addc_u32 s5, s75, 0
	v_mfma_f32_32x32x16_bf16 v[32:47], v[124:127], v[102:105], v[32:47]
	v_mfma_f32_32x32x16_bf16 v[16:31], v[124:127], v[106:109], v[16:31]
	v_mfma_f32_32x32x16_bf16 v[0:15], v[124:127], v[110:113], v[0:15]
	v_mfma_f32_32x32x16_bf16 v[48:63], v[124:127], v[132:135], v[48:63]
	ds_read_b128 v[102:105], v95 offset:12800
	ds_read_b128 v[106:109], v95 offset:15360
	ds_read_b128 v[110:113], v95 offset:17920
	ds_read_b128 v[120:123], v96
	ds_read_b128 v[124:127], v96 offset:32
	ds_read_b128 v[128:131], v95 offset:10240
	ds_read_b128 v[132:135], v95 offset:10272
	s_waitcnt lgkmcnt(3)
	v_mfma_f32_32x32x16_bf16 v[32:47], v[120:123], v[102:105], v[32:47]
	v_mfma_f32_32x32x16_bf16 v[16:31], v[120:123], v[106:109], v[16:31]
	v_mfma_f32_32x32x16_bf16 v[0:15], v[120:123], v[110:113], v[0:15]
	ds_read_b128 v[102:105], v95 offset:12832
	ds_read_b128 v[106:109], v95 offset:15392
	ds_read_b128 v[110:113], v95 offset:17952
	s_barrier
	s_waitcnt vmcnt(3)
	ds_write_b128 v93, v[80:83] offset:20480
	s_waitcnt vmcnt(2)
	ds_write_b128 v94, v[84:87] offset:20480
	s_waitcnt vmcnt(1)
	ds_write_b128 v93, v[88:91] offset:30720
	s_waitcnt vmcnt(0)
	ds_write_b128 v94, v[98:101] offset:30720
	s_waitcnt lgkmcnt(0)
	s_barrier
; #define MFMA(a, b, c) __builtin_amdgcn_mfma_f32_32x32x16_bf16((a), (b), (c), 0, 0, 0)
; template <int BM, int BN, int BK, int WAVES_M, int WAVES_N, int UNSWAP_FROM>
; DI void gemm_mainloop(const int tid, const bf16_t* __restrict__ A, int lda, const bf16_t* __restrict__ Bt, int ldb, int K, unsigned char* smem,
;                       f32x16 (&acc)[BM / WAVES_M / 32][BN / WAVES_N / 32]) {
;     ...
;     for (int kt = 0; kt < nk; ++kt) {
;         const int buf = kt & 1;
;         if (kt + 1 < nk) G_LOAD(kt + 1);
;         const unsigned char* sa_ = smem + buf * STAGE; const unsigned char* sb_ = sa_ + A_ST;
; #pragma unroll
;         for (int ks = 0; ks < BK / 16; ++ks) {
;             bf16x8 af[WM], bfr[WN];
; #pragma unroll
;             for (int i = 0; i < WM; ++i) af[i] = *(const bf16x8*)(sa_ + (((wm * WM + i) * 32 + r) * LS + ks * 16 + h * 8) * 2);
; #pragma unroll
;             for (int j = 0; j < WN; ++j) bfr[j] = *(const bf16x8*)(sb_ + (((wn * WN + j) * 32 + r) * LS + ks * 16 + h * 8) * 2);
; #pragma unroll
;             for (int i = 0; i < WM; ++i)
; #pragma unroll
;                 for (int j = 0; j < WN; ++j) {
;                     if (j < UNSWAP_FROM) acc[i][j] = MFMA(bfr[j], af[i], acc[i][j]);
;                     else acc[i][j] = MFMA(af[i], bfr[j], acc[i][j]);
;                 }
;         }
;         if (kt + 1 < nk) G_STORE(buf ^ 1);
;         __syncthreads();
	global_load_dwordx4 v[80:83], v[66:67], off offset:1408
	global_load_dwordx4 v[84:87], v[68:69], off offset:1408
	v_lshl_add_u64 v[88:89], s[4:5], 0, v[76:77]
	v_lshl_add_u64 v[88:89], v[88:89], 0, v[72:73]
	v_lshl_add_u64 v[98:99], s[4:5], 0, v[74:75]
	global_load_dwordx4 v[88:91], v[88:89], off
	v_lshl_add_u64 v[98:99], v[98:99], 0, v[70:71]
	global_load_dwordx4 v[98:101], v[98:99], off
	v_mfma_f32_32x32x16_bf16 v[48:63], v[120:123], v[128:131], v[48:63]
	s_add_u32 s4, s74, 0x101c0
	s_addc_u32 s5, s75, 0
	v_mfma_f32_32x32x16_bf16 v[32:47], v[124:127], v[102:105], v[32:47]
	v_mfma_f32_32x32x16_bf16 v[16:31], v[124:127], v[106:109], v[16:31]
	v_mfma_f32_32x32x16_bf16 v[0:15], v[124:127], v[110:113], v[0:15]
	v_mfma_f32_32x32x16_bf16 v[48:63], v[124:127], v[132:135], v[48:63]
	ds_read_b128 v[102:105], v95 offset:33280
	ds_read_b128 v[106:109], v95 offset:35840
	ds_read_b128 v[110:113], v95 offset:38400
	ds_read_b128 v[120:123], v96 offset:20480
	ds_read_b128 v[124:127], v96 offset:20512
	ds_read_b128 v[128:131], v95 offset:30720
	ds_read_b128 v[132:135], v95 offset:30752
	s_waitcnt lgkmcnt(3)
	v_mfma_f32_32x32x16_bf16 v[32:47], v[120:123], v[102:105], v[32:47]
	v_mfma_f32_32x32x16_bf16 v[16:31], v[120:123], v[106:109], v[16:31]
	v_mfma_f32_32x32x16_bf16 v[0:15], v[120:123], v[110:113], v[0:15]
	ds_read_b128 v[102:105], v95 offset:33312
	ds_read_b128 v[106:109], v95 offset:35872
	ds_read_b128 v[110:113], v95 offset:38432
	s_barrier
	s_waitcnt vmcnt(3)
	ds_write_b128 v93, v[80:83]
	s_waitcnt vmcnt(2)
	ds_write_b128 v94, v[84:87]
	s_waitcnt vmcnt(1)
	ds_write_b128 v93, v[88:91] offset:10240
	s_waitcnt vmcnt(0)
	ds_write_b128 v94, v[98:101] offset:10240
	s_waitcnt lgkmcnt(0)
	s_barrier
	global_load_dwordx4 v[80:83], v[66:67], off offset:1472
	global_load_dwordx4 v[84:87], v[68:69], off offset:1472
	v_lshl_add_u64 v[88:89], s[4:5], 0, v[76:77]
	v_lshl_add_u64 v[88:89], v[88:89], 0, v[72:73]
	v_lshl_add_u64 v[98:99], s[4:5], 0, v[74:75]
	global_load_dwordx4 v[88:91], v[88:89], off
	v_lshl_add_u64 v[98:99], v[98:99], 0, v[70:71]
	global_load_dwordx4 v[98:101], v[98:99], off
	v_mfma_f32_32x32x16_bf16 v[48:63], v[120:123], v[128:131], v[48:63]
	v_readlane_b32 s4, v244, 29
	v_readlane_b32 s5, v244, 30
	v_mfma_f32_32x32x16_bf16 v[32:47], v[124:127], v[102:105], v[32:47]
	v_mfma_f32_32x32x16_bf16 v[0:15], v[124:127], v[110:113], v[0:15]
	v_mfma_f32_32x32x16_bf16 v[16:31], v[124:127], v[106:109], v[16:31]
	v_mfma_f32_32x32x16_bf16 v[48:63], v[124:127], v[132:135], v[48:63]
	ds_read_b128 v[102:105], v95 offset:12800
	ds_read_b128 v[106:109], v95 offset:15360
	ds_read_b128 v[110:113], v95 offset:17920
	ds_read_b128 v[120:123], v96
	ds_read_b128 v[124:127], v96 offset:32
	ds_read_b128 v[128:131], v95 offset:10240
	ds_read_b128 v[132:135], v95 offset:10272
	s_waitcnt lgkmcnt(3)
	v_mfma_f32_32x32x16_bf16 v[32:47], v[120:123], v[102:105], v[32:47]
	v_mfma_f32_32x32x16_bf16 v[0:15], v[120:123], v[110:113], v[0:15]
	v_mfma_f32_32x32x16_bf16 v[16:31], v[120:123], v[106:109], v[16:31]
	ds_read_b128 v[102:105], v95 offset:12832
	ds_read_b128 v[106:109], v95 offset:15392
	ds_read_b128 v[110:113], v95 offset:17952
	s_barrier
	s_waitcnt vmcnt(3)
	ds_write_b128 v93, v[80:83] offset:20480
	s_waitcnt vmcnt(2)
	ds_write_b128 v94, v[84:87] offset:20480
	s_waitcnt vmcnt(1)
	ds_write_b128 v93, v[88:91] offset:30720
	s_waitcnt vmcnt(0)
	ds_write_b128 v94, v[98:101] offset:30720
	s_waitcnt lgkmcnt(6)
	v_mfma_f32_32x32x16_bf16 v[32:47], v[124:127], v[102:105], v[32:47]
	s_waitcnt lgkmcnt(0)
	s_barrier
	v_mfma_f32_32x32x16_bf16 v[0:15], v[124:127], v[110:113], v[0:15]
	v_mfma_f32_32x32x16_bf16 v[16:31], v[124:127], v[106:109], v[16:31]
	ds_read_b128 v[80:83], v95 offset:33280
	ds_read_b128 v[84:87], v95 offset:35840
	ds_read_b128 v[88:91], v95 offset:38400
	ds_read_b128 v[98:101], v96 offset:20480
	ds_read_b128 v[102:105], v96 offset:20512
	ds_read_b128 v[106:109], v95 offset:30720
	ds_read_b128 v[110:113], v95 offset:30752
	s_waitcnt lgkmcnt(3)
	v_mfma_f32_32x32x16_bf16 v[32:47], v[98:101], v[80:83], v[32:47]
	v_mfma_f32_32x32x16_bf16 v[0:15], v[98:101], v[88:91], v[0:15]
	v_mfma_f32_32x32x16_bf16 v[16:31], v[98:101], v[84:87], v[16:31]
	ds_read_b128 v[80:83], v95 offset:33312
	ds_read_b128 v[84:87], v95 offset:35872
	ds_read_b128 v[88:91], v95 offset:38432
	s_waitcnt lgkmcnt(0)
	s_barrier
	s_cmp_lg_u32 s10, 0
	s_cbranch_scc1 .Lkv_stg_end0
	s_barrier
; DI unsigned pk2(float a, float b) { f2_t v = {a, b}; bf2_t r = __builtin_convertvector(v, bf2_t); return __builtin_bit_cast(unsigned, r); }
; DI void kv_tile(const Params& p, int mt, int hd, unsigned char* smem) {
;     ...
; #pragma unroll
;     for (int g = 0; g < 4; ++g) {
;         const f32x4 q4 = *(const f32x4*)(ssq + mw + 8 * g + 4 * h);
;         const float r0 = rsqrtf(q4.x * (1.f / 256.f) + EPS), r1 = rsqrtf(q4.y * (1.f / 256.f) + EPS);
;         const float r2 = rsqrtf(q4.z * (1.f / 256.f) + EPS), r3 = rsqrtf(q4.w * (1.f / 256.f) + EPS);
; #pragma unroll
;         for (int j = 0; j < 4; ++j) {
;             u32x2 o; o.x = pk2(acc[0][j][4 * g] * r0, acc[0][j][4 * g + 1] * r1); o.y = pk2(acc[0][j][4 * g + 2] * r2, acc[0][j][4 * g + 3] * r3);
;             *(u32x2*)(Vt + ((size_t)bh * 128 + j * 32 + r) * SEQ_ + sw + 8 * g + 4 * h) = o;
;         }
;     }
.Lkv_stg_end0:
	v_mfma_f32_32x32x16_bf16 v[32:47], v[102:105], v[80:83], v[32:47]
	v_lshl_add_u64 v[80:81], v[64:65], 2, s[76:77]
	v_lshrrev_b32_e32 v65, 3, v79
	v_and_b32_e32 v65, 4, v65
	v_lshlrev_b32_e32 v116, 2, v65
	v_lshl_add_u64 v[82:83], v[80:81], 0, v[116:117]
	v_lshlrev_b32_e32 v80, 1, v97
	v_mov_b32_e32 v81, v117
	v_mfma_f32_32x32x16_bf16 v[0:15], v[102:105], v[88:91], v[0:15]
	global_load_dwordx4 v[88:91], v[82:83], off
	v_ashrrev_i32_e32 v79, 31, v78
	v_or_b32_e32 v64, v64, v92
	v_mfma_f32_32x32x16_bf16 v[48:63], v[120:123], v[128:131], v[48:63]
	v_mfma_f32_32x32x16_bf16 v[48:63], v[124:127], v[132:135], v[48:63]
	v_mfma_f32_32x32x16_bf16 v[48:63], v[98:101], v[106:109], v[48:63]
	v_mfma_f32_32x32x16_bf16 v[16:31], v[102:105], v[84:87], v[16:31]
	v_mov_b64_e32 v[86:87], s[48:49]
	v_lshl_add_u64 v[84:85], s[4:5], 0, v[80:81]
	v_lshlrev_b32_e32 v80, 1, v65
	v_lshl_add_u64 v[84:85], v[84:85], 0, v[80:81]
	s_waitcnt vmcnt(0)
	v_pk_fma_f32 v[88:89], v[88:89], s[46:47], v[86:87] op_sel_hi:[1,0,0]
	s_nop 0
	v_mul_f32_e32 v65, 0x4b800000, v88
	v_cmp_gt_f32_e64 s[4:5], s53, v88
	v_mfma_f32_32x32x16_bf16 v[48:63], v[102:105], v[110:113], v[48:63]
	v_cmp_gt_f32_e32 vcc, s53, v89
	v_cndmask_b32_e64 v65, v88, v65, s[4:5]
	v_rsq_f32_e32 v88, v65
	v_mul_f32_e32 v65, 0x4b800000, v89
	v_cndmask_b32_e32 v65, v89, v65, vcc
	v_rsq_f32_e32 v89, v65
	s_nop 0
	v_pk_mul_f32 v[98:99], v[88:89], s[50:51] op_sel_hi:[1,0]
	s_nop 0
	v_cndmask_b32_e32 v89, v89, v99, vcc
	v_cndmask_b32_e64 v88, v88, v98, s[4:5]
	s_nop 0
	v_pk_mul_f32 v[48:49], v[48:49], v[88:89]
	v_pk_mul_f32 v[32:33], v[32:33], v[88:89]
	v_cvt_pk_bf16_f32 v98, v48, v49
	v_pk_fma_f32 v[48:49], v[90:91], s[46:47], v[86:87] op_sel_hi:[1,0,0]
	v_pk_mul_f32 v[16:17], v[16:17], v[88:89]
	v_mul_f32_e32 v65, 0x4b800000, v48
	v_cmp_gt_f32_e64 s[4:5], s53, v48
	v_cmp_gt_f32_e32 vcc, s53, v49
	v_pk_mul_f32 v[0:1], v[0:1], v[88:89]
	v_cndmask_b32_e64 v48, v48, v65, s[4:5]
	v_mul_f32_e32 v65, 0x4b800000, v49
	v_cndmask_b32_e32 v49, v49, v65, vcc
	v_rsq_f32_e32 v48, v48
	v_rsq_f32_e32 v49, v49
	v_cvt_pk_bf16_f32 v0, v0, v1
	v_ashrrev_i32_e32 v65, 31, v64
	v_pk_mul_f32 v[90:91], v[48:49], s[50:51] op_sel_hi:[1,0]
	s_nop 0
	v_cndmask_b32_e32 v91, v49, v91, vcc
	v_cndmask_b32_e64 v90, v48, v90, s[4:5]
	v_pk_mul_f32 v[48:49], v[50:51], v[90:91]
	v_pk_mul_f32 v[2:3], v[2:3], v[90:91]
	v_cvt_pk_bf16_f32 v99, v48, v49
	v_lshlrev_b64 v[48:49], 21, v[78:79]
	v_lshl_or_b32 v48, v92, 14, v48
	v_lshl_add_u64 v[50:51], v[84:85], 0, v[48:49]
	global_store_dwordx2 v[50:51], v[98:99], off
	v_cvt_pk_bf16_f32 v98, v32, v33
	v_pk_mul_f32 v[32:33], v[34:35], v[90:91]
	v_cvt_pk_bf16_f32 v1, v2, v3
	v_cvt_pk_bf16_f32 v99, v32, v33
	v_or_b32_e32 v32, 0x80000, v48
	v_mov_b32_e32 v33, v49
	v_lshl_add_u64 v[34:35], v[84:85], 0, v[32:33]
	global_store_dwordx2 v[34:35], v[98:99], off
	v_cvt_pk_bf16_f32 v34, v16, v17
	v_pk_mul_f32 v[16:17], v[18:19], v[90:91]
	s_nop 0
	v_cvt_pk_bf16_f32 v35, v16, v17
	v_or_b32_e32 v16, 0x100000, v48
	v_mov_b32_e32 v17, v49
	v_or_b32_e32 v48, 0x180000, v48
	v_lshl_add_u64 v[18:19], v[84:85], 0, v[16:17]
	v_lshl_add_u64 v[2:3], v[84:85], 0, v[48:49]
	global_store_dwordx2 v[18:19], v[34:35], off
	global_store_dwordx2 v[2:3], v[0:1], off
	global_load_dwordx4 v[88:91], v[82:83], off offset:32
	v_lshl_add_u64 v[0:1], v[84:85], 0, 16
	s_waitcnt vmcnt(0)
	v_pk_fma_f32 v[2:3], v[88:89], s[46:47], v[86:87] op_sel_hi:[1,0,0]
	s_nop 0
	v_mul_f32_e32 v18, 0x4b800000, v2
	v_cmp_gt_f32_e64 s[4:5], s53, v2
	v_cmp_gt_f32_e32 vcc, s53, v3
	s_nop 0
	v_cndmask_b32_e64 v2, v2, v18, s[4:5]
	v_mul_f32_e32 v18, 0x4b800000, v3
	v_cndmask_b32_e32 v3, v3, v18, vcc
	v_rsq_f32_e32 v2, v2
	v_rsq_f32_e32 v3, v3
	s_nop 0
	v_pk_mul_f32 v[18:19], v[2:3], s[50:51] op_sel_hi:[1,0]
	s_nop 0
	v_cndmask_b32_e32 v3, v3, v19, vcc
	v_cndmask_b32_e64 v2, v2, v18, s[4:5]
	v_pk_mul_f32 v[18:19], v[52:53], v[2:3]
	v_pk_mul_f32 v[20:21], v[20:21], v[2:3]
	v_cvt_pk_bf16_f32 v34, v18, v19
	v_pk_fma_f32 v[18:19], v[90:91], s[46:47], v[86:87] op_sel_hi:[1,0,0]
	v_cvt_pk_bf16_f32 v20, v20, v21
	v_mul_f32_e32 v35, 0x4b800000, v18
	v_cmp_gt_f32_e64 s[4:5], s53, v18
	v_cmp_gt_f32_e32 vcc, s53, v19
	s_nop 0
	v_cndmask_b32_e64 v18, v18, v35, s[4:5]
	v_mul_f32_e32 v35, 0x4b800000, v19
	v_cndmask_b32_e32 v19, v19, v35, vcc
	v_rsq_f32_e32 v18, v18
	v_rsq_f32_e32 v19, v19
	s_nop 0
	v_pk_mul_f32 v[52:53], v[18:19], s[50:51] op_sel_hi:[1,0]
	s_nop 0
	v_cndmask_b32_e32 v19, v19, v53, vcc
	v_cndmask_b32_e64 v18, v18, v52, s[4:5]
	v_pk_mul_f32 v[52:53], v[54:55], v[18:19]
	v_pk_mul_f32 v[22:23], v[22:23], v[18:19]
	v_cvt_pk_bf16_f32 v35, v52, v53
	global_store_dwordx2 v[50:51], v[34:35], off offset:16
	v_pk_mul_f32 v[34:35], v[36:37], v[2:3]
	v_pk_mul_f32 v[36:37], v[38:39], v[18:19]
	v_pk_mul_f32 v[2:3], v[4:5], v[2:3]
	v_pk_mul_f32 v[4:5], v[6:7], v[18:19]
	v_cvt_pk_bf16_f32 v34, v34, v35
	v_cvt_pk_bf16_f32 v35, v36, v37
	v_lshl_add_u64 v[36:37], v[0:1], 0, v[32:33]
	v_cvt_pk_bf16_f32 v21, v22, v23
	v_lshl_add_u64 v[22:23], v[0:1], 0, v[16:17]
	v_cvt_pk_bf16_f32 v2, v2, v3
	v_cvt_pk_bf16_f32 v3, v4, v5
	v_lshl_add_u64 v[0:1], v[0:1], 0, v[48:49]
	global_store_dwordx2 v[36:37], v[34:35], off
	global_store_dwordx2 v[22:23], v[20:21], off
	global_store_dwordx2 v[0:1], v[2:3], off
	global_load_dwordx4 v[2:5], v[82:83], off offset:64
	v_lshl_add_u64 v[0:1], v[84:85], 0, 32
	s_waitcnt vmcnt(0)
; DI unsigned pk2(float a, float b) { f2_t v = {a, b}; bf2_t r = __builtin_convertvector(v, bf2_t); return __builtin_bit_cast(unsigned, r); }
; template <int BM, int BN, int BK, int WAVES_M, int WAVES_N, int UNSWAP_FROM>
; DI void gemm_mainloop(const int tid, const bf16_t* __restrict__ A, int lda, const bf16_t* __restrict__ Bt, int ldb, int K, unsigned char* smem,
;                       f32x16 (&acc)[BM / WAVES_M / 32][BN / WAVES_N / 32]) {
;     ...
;     const int nk = K / BK;
;     ...
;     G_LOAD(0); G_STORE(0); __syncthreads();
; DI void kv_tile(const Params& p, int mt, int hd, unsigned char* smem) {
;     ...
;     for (int g = 0; g < 4; ++g) {
;         const f32x4 q4 = *(const f32x4*)(ssq + mw + 8 * g + 4 * h);
;         const float r0 = rsqrtf(q4.x * (1.f / 256.f) + EPS), r1 = rsqrtf(q4.y * (1.f / 256.f) + EPS);
;         const float r2 = rsqrtf(q4.z * (1.f / 256.f) + EPS), r3 = rsqrtf(q4.w * (1.f / 256.f) + EPS);
; #pragma unroll
;         for (int j = 0; j < 4; ++j) {
;             u32x2 o; o.x = pk2(acc[0][j][4 * g] * r0, acc[0][j][4 * g + 1] * r1); o.y = pk2(acc[0][j][4 * g + 2] * r2, acc[0][j][4 * g + 3] * r3);
;             *(u32x2*)(Vt + ((size_t)bh * 128 + j * 32 + r) * SEQ_ + sw + 8 * g + 4 * h) = o;
;         }
;     }
	v_pk_fma_f32 v[2:3], v[2:3], s[46:47], v[86:87] op_sel_hi:[1,0,0]
	s_nop 0
	v_mul_f32_e32 v6, 0x4b800000, v2
	v_cmp_gt_f32_e64 s[4:5], s53, v2
	v_cmp_gt_f32_e32 vcc, s53, v3
	v_pk_fma_f32 v[4:5], v[4:5], s[46:47], v[86:87] op_sel_hi:[1,0,0]
	v_cndmask_b32_e64 v2, v2, v6, s[4:5]
	v_mul_f32_e32 v6, 0x4b800000, v3
	v_cndmask_b32_e32 v3, v3, v6, vcc
	v_rsq_f32_e32 v2, v2
	v_rsq_f32_e32 v3, v3
	s_nop 0
	v_pk_mul_f32 v[6:7], v[2:3], s[50:51] op_sel_hi:[1,0]
	s_nop 0
	v_cndmask_b32_e32 v3, v3, v7, vcc
	v_cndmask_b32_e64 v2, v2, v6, s[4:5]
	v_pk_mul_f32 v[6:7], v[56:57], v[2:3]
	v_cmp_gt_f32_e64 s[4:5], s53, v4
	v_cvt_pk_bf16_f32 v6, v6, v7
	v_mul_f32_e32 v7, 0x4b800000, v4
	v_cmp_gt_f32_e32 vcc, s53, v5
	v_cndmask_b32_e64 v4, v4, v7, s[4:5]
	v_mul_f32_e32 v7, 0x4b800000, v5
	v_cndmask_b32_e32 v5, v5, v7, vcc
	v_rsq_f32_e32 v4, v4
	v_rsq_f32_e32 v5, v5
	s_nop 0
	v_pk_mul_f32 v[18:19], v[4:5], s[50:51] op_sel_hi:[1,0]
	s_nop 0
	v_cndmask_b32_e32 v5, v5, v19, vcc
	v_cndmask_b32_e64 v4, v4, v18, s[4:5]
	v_pk_mul_f32 v[18:19], v[58:59], v[4:5]
	s_nop 0
	v_cvt_pk_bf16_f32 v7, v18, v19
	global_store_dwordx2 v[50:51], v[6:7], off offset:32
	v_pk_mul_f32 v[6:7], v[40:41], v[2:3]
	v_pk_mul_f32 v[18:19], v[42:43], v[4:5]
	v_cvt_pk_bf16_f32 v6, v6, v7
	v_cvt_pk_bf16_f32 v7, v18, v19
	v_lshl_add_u64 v[18:19], v[0:1], 0, v[32:33]
	global_store_dwordx2 v[18:19], v[6:7], off
	v_pk_mul_f32 v[6:7], v[24:25], v[2:3]
	v_pk_mul_f32 v[18:19], v[26:27], v[4:5]
	v_pk_mul_f32 v[2:3], v[8:9], v[2:3]
	v_pk_mul_f32 v[4:5], v[10:11], v[4:5]
	v_cvt_pk_bf16_f32 v6, v6, v7
	v_cvt_pk_bf16_f32 v7, v18, v19
	v_lshl_add_u64 v[18:19], v[0:1], 0, v[16:17]
	v_cvt_pk_bf16_f32 v2, v2, v3
	v_cvt_pk_bf16_f32 v3, v4, v5
	v_lshl_add_u64 v[0:1], v[0:1], 0, v[48:49]
	global_store_dwordx2 v[18:19], v[6:7], off
	global_store_dwordx2 v[0:1], v[2:3], off
	global_load_dwordx4 v[0:3], v[82:83], off offset:96
	v_lshl_add_u64 v[4:5], v[84:85], 0, 48
	s_waitcnt vmcnt(0)
	v_pk_fma_f32 v[0:1], v[0:1], s[46:47], v[86:87] op_sel_hi:[1,0,0]
	s_nop 0
	v_mul_f32_e32 v6, 0x4b800000, v0
	v_cmp_gt_f32_e64 s[4:5], s53, v0
	v_cmp_gt_f32_e32 vcc, s53, v1
	v_pk_fma_f32 v[2:3], v[2:3], s[46:47], v[86:87] op_sel_hi:[1,0,0]
	v_cndmask_b32_e64 v0, v0, v6, s[4:5]
	v_mul_f32_e32 v6, 0x4b800000, v1
	v_cndmask_b32_e32 v1, v1, v6, vcc
	v_rsq_f32_e32 v0, v0
	v_rsq_f32_e32 v1, v1
	s_nop 0
	v_pk_mul_f32 v[6:7], v[0:1], s[50:51] op_sel_hi:[1,0]
	s_nop 0
	v_cndmask_b32_e32 v1, v1, v7, vcc
	v_cndmask_b32_e64 v0, v0, v6, s[4:5]
	v_pk_mul_f32 v[6:7], v[60:61], v[0:1]
	v_cmp_gt_f32_e64 s[4:5], s53, v2
	v_cvt_pk_bf16_f32 v6, v6, v7
	v_mul_f32_e32 v7, 0x4b800000, v2
	v_cmp_gt_f32_e32 vcc, s53, v3
	v_cndmask_b32_e64 v2, v2, v7, s[4:5]
	v_mul_f32_e32 v7, 0x4b800000, v3
	v_cndmask_b32_e32 v3, v3, v7, vcc
	v_rsq_f32_e32 v2, v2
	v_rsq_f32_e32 v3, v3
	s_nop 0
	v_pk_mul_f32 v[8:9], v[2:3], s[50:51] op_sel_hi:[1,0]
	s_nop 0
	v_cndmask_b32_e32 v3, v3, v9, vcc
	v_cndmask_b32_e64 v2, v2, v8, s[4:5]
	v_pk_mul_f32 v[8:9], v[62:63], v[2:3]
	s_nop 0
	v_cvt_pk_bf16_f32 v7, v8, v9
	global_store_dwordx2 v[50:51], v[6:7], off offset:48
	v_pk_mul_f32 v[6:7], v[44:45], v[0:1]
	v_pk_mul_f32 v[8:9], v[46:47], v[2:3]
	v_cvt_pk_bf16_f32 v6, v6, v7
	v_cvt_pk_bf16_f32 v7, v8, v9
	v_lshl_add_u64 v[8:9], v[4:5], 0, v[32:33]
	global_store_dwordx2 v[8:9], v[6:7], off
	v_pk_mul_f32 v[6:7], v[28:29], v[0:1]
	v_pk_mul_f32 v[8:9], v[30:31], v[2:3]
	v_pk_mul_f32 v[0:1], v[12:13], v[0:1]
	v_pk_mul_f32 v[2:3], v[14:15], v[2:3]
	v_cvt_pk_bf16_f32 v6, v6, v7
	v_cvt_pk_bf16_f32 v7, v8, v9
	v_lshl_add_u64 v[8:9], v[4:5], 0, v[16:17]
	v_cvt_pk_bf16_f32 v0, v0, v1
	v_cvt_pk_bf16_f32 v1, v2, v3
	v_lshl_add_u64 v[2:3], v[4:5], 0, v[48:49]
	global_store_dwordx2 v[8:9], v[6:7], off
	global_store_dwordx2 v[2:3], v[0:1], off
	global_load_dwordx4 v[0:3], v[66:67], off offset:1024
	s_nop 0
	global_load_dwordx4 v[4:7], v[68:69], off offset:1024
	v_lshl_add_u64 v[8:9], s[74:75], 0, v[76:77]
	v_lshl_add_u64 v[72:73], v[8:9], 0, v[72:73]
	v_lshl_add_u64 v[12:13], s[74:75], 0, v[74:75]
	global_load_dwordx4 v[8:11], v[72:73], off
	v_lshl_add_u64 v[70:71], v[12:13], 0, v[70:71]
	global_load_dwordx4 v[12:15], v[70:71], off
	s_waitcnt vmcnt(3)
	ds_write_b128 v93, v[0:3]
	s_waitcnt vmcnt(2)
	ds_write_b128 v94, v[4:7]
	s_waitcnt vmcnt(1)
	ds_write_b128 v93, v[8:11] offset:10240
	s_waitcnt vmcnt(0)
	ds_write_b128 v94, v[12:15] offset:10240
	s_waitcnt lgkmcnt(0)
	s_barrier
	s_cmp_eq_u32 s10, 0
	s_cbranch_scc1 .Lkv_stg_beg1
	s_barrier
; #define MFMA(a, b, c) __builtin_amdgcn_mfma_f32_32x32x16_bf16((a), (b), (c), 0, 0, 0)
; template <int BM, int BN, int BK, int WAVES_M, int WAVES_N, int UNSWAP_FROM>
; DI void gemm_mainloop(const int tid, const bf16_t* __restrict__ A, int lda, const bf16_t* __restrict__ Bt, int ldb, int K, unsigned char* smem,
;                       f32x16 (&acc)[BM / WAVES_M / 32][BN / WAVES_N / 32]) {
;     ...
;     for (int kt = 0; kt < nk; ++kt) {
;         const int buf = kt & 1;
;         if (kt + 1 < nk) G_LOAD(kt + 1);
;         const unsigned char* sa_ = smem + buf * STAGE; const unsigned char* sb_ = sa_ + A_ST;
; #pragma unroll
;         for (int ks = 0; ks < BK / 16; ++ks) {
;             bf16x8 af[WM], bfr[WN];
; #pragma unroll
;             for (int i = 0; i < WM; ++i) af[i] = *(const bf16x8*)(sa_ + (((wm * WM + i) * 32 + r) * LS + ks * 16 + h * 8) * 2);
; #pragma unroll
;             for (int j = 0; j < WN; ++j) bfr[j] = *(const bf16x8*)(sb_ + (((wn * WN + j) * 32 + r) * LS + ks * 16 + h * 8) * 2);
; #pragma unroll
;             for (int i = 0; i < WM; ++i)
; #pragma unroll
;                 for (int j = 0; j < WN; ++j) {
;                     if (j < UNSWAP_FROM) acc[i][j] = MFMA(bfr[j], af[i], acc[i][j]);
;                     else acc[i][j] = MFMA(af[i], bfr[j], acc[i][j]);
;                 }
;         }
;         if (kt + 1 < nk) G_STORE(buf ^ 1);
;         __syncthreads();
.Lkv_stg_beg1:
	global_load_dwordx4 v[74:77], v[66:67], off offset:1088
	global_load_dwordx4 v[82:85], v[68:69], off offset:1088
	global_load_dwordx4 v[86:89], v[72:73], off offset:64
	global_load_dwordx4 v[98:101], v[70:71], off offset:64
	ds_read_b128 v[0:3], v95 offset:12800
	ds_read_b128 v[4:7], v95 offset:15360
	ds_read_b128 v[8:11], v95 offset:17920
	ds_read_b128 v[12:15], v96
	ds_read_b128 v[102:105], v96 offset:32
	ds_read_b128 v[16:19], v95 offset:10240
	ds_read_b128 v[106:109], v95 offset:10272
	ds_read_b128 v[110:113], v95 offset:12832
	ds_read_b128 v[120:123], v95 offset:15392
	ds_read_b128 v[124:127], v95 offset:17952
	s_barrier
	s_waitcnt vmcnt(3)
	ds_write_b128 v93, v[74:77] offset:20480
	s_waitcnt vmcnt(2)
	ds_write_b128 v94, v[82:85] offset:20480
	s_waitcnt vmcnt(1)
	ds_write_b128 v93, v[86:89] offset:30720
	s_waitcnt vmcnt(0)
	ds_write_b128 v94, v[98:101] offset:30720
	s_waitcnt lgkmcnt(0)
	s_barrier
	global_load_dwordx4 v[74:77], v[66:67], off offset:1152
	global_load_dwordx4 v[82:85], v[68:69], off offset:1152
	global_load_dwordx4 v[86:89], v[72:73], off offset:128
	global_load_dwordx4 v[98:101], v[70:71], off offset:128
	v_mfma_f32_32x32x16_bf16 v[48:63], v[16:19], v[12:15], 0
	v_mfma_f32_32x32x16_bf16 v[32:47], v[0:3], v[12:15], 0
	v_mfma_f32_32x32x16_bf16 v[16:31], v[4:7], v[12:15], 0
	v_mfma_f32_32x32x16_bf16 v[0:15], v[8:11], v[12:15], 0
	v_mfma_f32_32x32x16_bf16 v[32:47], v[110:113], v[102:105], v[32:47]
	v_mfma_f32_32x32x16_bf16 v[16:31], v[120:123], v[102:105], v[16:31]
	v_mfma_f32_32x32x16_bf16 v[0:15], v[124:127], v[102:105], v[0:15]
	v_mfma_f32_32x32x16_bf16 v[48:63], v[106:109], v[102:105], v[48:63]
	ds_read_b128 v[102:105], v95 offset:33280
	ds_read_b128 v[106:109], v95 offset:35840
	ds_read_b128 v[110:113], v95 offset:38400
	ds_read_b128 v[120:123], v96 offset:20480
	ds_read_b128 v[124:127], v96 offset:20512
	ds_read_b128 v[128:131], v95 offset:30720
	ds_read_b128 v[132:135], v95 offset:30752
	s_waitcnt lgkmcnt(3)
	v_mfma_f32_32x32x16_bf16 v[32:47], v[102:105], v[120:123], v[32:47]
	v_mfma_f32_32x32x16_bf16 v[16:31], v[106:109], v[120:123], v[16:31]
	v_mfma_f32_32x32x16_bf16 v[0:15], v[110:113], v[120:123], v[0:15]
	ds_read_b128 v[102:105], v95 offset:33312
	ds_read_b128 v[106:109], v95 offset:35872
	ds_read_b128 v[110:113], v95 offset:38432
	s_barrier
	s_waitcnt vmcnt(3)
	ds_write_b128 v93, v[74:77]
	s_waitcnt vmcnt(2)
	ds_write_b128 v94, v[82:85]
	s_waitcnt vmcnt(1)
	ds_write_b128 v93, v[86:89] offset:10240
	s_waitcnt vmcnt(0)
	ds_write_b128 v94, v[98:101] offset:10240
	s_waitcnt lgkmcnt(0)
	s_barrier
	global_load_dwordx4 v[74:77], v[66:67], off offset:1216
	global_load_dwordx4 v[82:85], v[68:69], off offset:1216
	global_load_dwordx4 v[86:89], v[72:73], off offset:192
	global_load_dwordx4 v[98:101], v[70:71], off offset:192
	v_mfma_f32_32x32x16_bf16 v[48:63], v[128:131], v[120:123], v[48:63]
	v_mfma_f32_32x32x16_bf16 v[32:47], v[102:105], v[124:127], v[32:47]
	v_mfma_f32_32x32x16_bf16 v[16:31], v[106:109], v[124:127], v[16:31]
	v_mfma_f32_32x32x16_bf16 v[0:15], v[110:113], v[124:127], v[0:15]
	v_mfma_f32_32x32x16_bf16 v[48:63], v[132:135], v[124:127], v[48:63]
	ds_read_b128 v[102:105], v95 offset:12800
	ds_read_b128 v[106:109], v95 offset:15360
	ds_read_b128 v[110:113], v95 offset:17920
	ds_read_b128 v[120:123], v96
	ds_read_b128 v[124:127], v96 offset:32
	ds_read_b128 v[128:131], v95 offset:10240
	ds_read_b128 v[132:135], v95 offset:10272
	s_waitcnt lgkmcnt(3)
	v_mfma_f32_32x32x16_bf16 v[32:47], v[102:105], v[120:123], v[32:47]
	v_mfma_f32_32x32x16_bf16 v[16:31], v[106:109], v[120:123], v[16:31]
	v_mfma_f32_32x32x16_bf16 v[0:15], v[110:113], v[120:123], v[0:15]
	ds_read_b128 v[102:105], v95 offset:12832
	ds_read_b128 v[106:109], v95 offset:15392
	ds_read_b128 v[110:113], v95 offset:17952
	s_barrier
	s_waitcnt vmcnt(3)
	ds_write_b128 v93, v[74:77] offset:20480
	s_waitcnt vmcnt(2)
	ds_write_b128 v94, v[82:85] offset:20480
	s_waitcnt vmcnt(1)
	ds_write_b128 v93, v[86:89] offset:30720
	s_waitcnt vmcnt(0)
	ds_write_b128 v94, v[98:101] offset:30720
	s_waitcnt lgkmcnt(0)
	s_barrier
	global_load_dwordx4 v[74:77], v[66:67], off offset:1280
	global_load_dwordx4 v[82:85], v[68:69], off offset:1280
	global_load_dwordx4 v[86:89], v[72:73], off offset:256
	global_load_dwordx4 v[98:101], v[70:71], off offset:256
	v_mfma_f32_32x32x16_bf16 v[48:63], v[128:131], v[120:123], v[48:63]
	v_mfma_f32_32x32x16_bf16 v[32:47], v[102:105], v[124:127], v[32:47]
	v_mfma_f32_32x32x16_bf16 v[16:31], v[106:109], v[124:127], v[16:31]
	v_mfma_f32_32x32x16_bf16 v[0:15], v[110:113], v[124:127], v[0:15]
	v_mfma_f32_32x32x16_bf16 v[48:63], v[132:135], v[124:127], v[48:63]
	ds_read_b128 v[102:105], v95 offset:33280
	ds_read_b128 v[106:109], v95 offset:35840
	ds_read_b128 v[110:113], v95 offset:38400
	ds_read_b128 v[120:123], v96 offset:20480
	ds_read_b128 v[124:127], v96 offset:20512
	ds_read_b128 v[128:131], v95 offset:30720
	ds_read_b128 v[132:135], v95 offset:30752
	s_waitcnt lgkmcnt(3)
	v_mfma_f32_32x32x16_bf16 v[32:47], v[102:105], v[120:123], v[32:47]
	v_mfma_f32_32x32x16_bf16 v[16:31], v[106:109], v[120:123], v[16:31]
	v_mfma_f32_32x32x16_bf16 v[0:15], v[110:113], v[120:123], v[0:15]
	ds_read_b128 v[102:105], v95 offset:33312
	ds_read_b128 v[106:109], v95 offset:35872
	ds_read_b128 v[110:113], v95 offset:38432
	s_barrier
	s_waitcnt vmcnt(3)
	ds_write_b128 v93, v[74:77]
	s_waitcnt vmcnt(2)
	ds_write_b128 v94, v[82:85]
	s_waitcnt vmcnt(1)
	ds_write_b128 v93, v[86:89] offset:10240
	s_waitcnt vmcnt(0)
	ds_write_b128 v94, v[98:101] offset:10240
	s_waitcnt lgkmcnt(0)
	s_barrier
; #define MFMA(a, b, c) __builtin_amdgcn_mfma_f32_32x32x16_bf16((a), (b), (c), 0, 0, 0)
; template <int BM, int BN, int BK, int WAVES_M, int WAVES_N, int UNSWAP_FROM>
; DI void gemm_mainloop(const int tid, const bf16_t* __restrict__ A, int lda, const bf16_t* __restrict__ Bt, int ldb, int K, unsigned char* smem,
;                       f32x16 (&acc)[BM / WAVES_M / 32][BN / WAVES_N / 32]) {
;     ...
;     for (int kt = 0; kt < nk; ++kt) {
;         const int buf = kt & 1;
;         if (kt + 1 < nk) G_LOAD(kt + 1);
;         const unsigned char* sa_ = smem + buf * STAGE; const unsigned char* sb_ = sa_ + A_ST;
; #pragma unroll
;         for (int ks = 0; ks < BK / 16; ++ks) {
;             bf16x8 af[WM], bfr[WN];
; #pragma unroll
;             for (int i = 0; i < WM; ++i) af[i] = *(const bf16x8*)(sa_ + (((wm * WM + i) * 32 + r) * LS + ks * 16 + h * 8) * 2);
; #pragma unroll
;             for (int j = 0; j < WN; ++j) bfr[j] = *(const bf16x8*)(sb_ + (((wn * WN + j) * 32 + r) * LS + ks * 16 + h * 8) * 2);
; #pragma unroll
;             for (int i = 0; i < WM; ++i)
; #pragma unroll
;                 for (int j = 0; j < WN; ++j) {
;                     if (j < UNSWAP_FROM) acc[i][j] = MFMA(bfr[j], af[i], acc[i][j]);
;                     else acc[i][j] = MFMA(af[i], bfr[j], acc[i][j]);
;                 }
;         }
;         if (kt + 1 < nk) G_STORE(buf ^ 1);
;         __syncthreads();
	global_load_dwordx4 v[74:77], v[66:67], off offset:1344
	global_load_dwordx4 v[82:85], v[68:69], off offset:1344
	global_load_dwordx4 v[86:89], v[72:73], off offset:320
	global_load_dwordx4 v[98:101], v[70:71], off offset:320
	v_mfma_f32_32x32x16_bf16 v[48:63], v[128:131], v[120:123], v[48:63]
	v_mfma_f32_32x32x16_bf16 v[32:47], v[102:105], v[124:127], v[32:47]
	v_mfma_f32_32x32x16_bf16 v[16:31], v[106:109], v[124:127], v[16:31]
	v_mfma_f32_32x32x16_bf16 v[0:15], v[110:113], v[124:127], v[0:15]
	v_mfma_f32_32x32x16_bf16 v[48:63], v[132:135], v[124:127], v[48:63]
	ds_read_b128 v[102:105], v95 offset:12800
	ds_read_b128 v[106:109], v95 offset:15360
	ds_read_b128 v[110:113], v95 offset:17920
	ds_read_b128 v[120:123], v96
	ds_read_b128 v[124:127], v96 offset:32
	ds_read_b128 v[128:131], v95 offset:10240
	ds_read_b128 v[132:135], v95 offset:10272
	s_waitcnt lgkmcnt(3)
	v_mfma_f32_32x32x16_bf16 v[32:47], v[102:105], v[120:123], v[32:47]
	v_mfma_f32_32x32x16_bf16 v[16:31], v[106:109], v[120:123], v[16:31]
	v_mfma_f32_32x32x16_bf16 v[0:15], v[110:113], v[120:123], v[0:15]
	ds_read_b128 v[102:105], v95 offset:12832
	ds_read_b128 v[106:109], v95 offset:15392
	ds_read_b128 v[110:113], v95 offset:17952
	s_barrier
	s_waitcnt vmcnt(3)
	ds_write_b128 v93, v[74:77] offset:20480
	s_waitcnt vmcnt(2)
	ds_write_b128 v94, v[82:85] offset:20480
	s_waitcnt vmcnt(1)
	ds_write_b128 v93, v[86:89] offset:30720
	s_waitcnt vmcnt(0)
	ds_write_b128 v94, v[98:101] offset:30720
	s_waitcnt lgkmcnt(0)
	s_barrier
	global_load_dwordx4 v[74:77], v[66:67], off offset:1408
	global_load_dwordx4 v[82:85], v[68:69], off offset:1408
	global_load_dwordx4 v[86:89], v[72:73], off offset:384
	global_load_dwordx4 v[98:101], v[70:71], off offset:384
	v_mfma_f32_32x32x16_bf16 v[48:63], v[128:131], v[120:123], v[48:63]
	v_mfma_f32_32x32x16_bf16 v[32:47], v[102:105], v[124:127], v[32:47]
	v_mfma_f32_32x32x16_bf16 v[16:31], v[106:109], v[124:127], v[16:31]
	v_mfma_f32_32x32x16_bf16 v[0:15], v[110:113], v[124:127], v[0:15]
	v_mfma_f32_32x32x16_bf16 v[48:63], v[132:135], v[124:127], v[48:63]
	ds_read_b128 v[102:105], v95 offset:33280
	ds_read_b128 v[106:109], v95 offset:35840
	ds_read_b128 v[110:113], v95 offset:38400
	ds_read_b128 v[120:123], v96 offset:20480
	ds_read_b128 v[124:127], v96 offset:20512
	ds_read_b128 v[128:131], v95 offset:30720
	ds_read_b128 v[132:135], v95 offset:30752
	s_waitcnt lgkmcnt(3)
	v_mfma_f32_32x32x16_bf16 v[32:47], v[102:105], v[120:123], v[32:47]
	v_mfma_f32_32x32x16_bf16 v[16:31], v[106:109], v[120:123], v[16:31]
	v_mfma_f32_32x32x16_bf16 v[0:15], v[110:113], v[120:123], v[0:15]
	ds_read_b128 v[102:105], v95 offset:33312
	ds_read_b128 v[106:109], v95 offset:35872
	ds_read_b128 v[110:113], v95 offset:38432
	s_barrier
	s_waitcnt vmcnt(3)
	ds_write_b128 v93, v[74:77]
	s_waitcnt vmcnt(2)
	ds_write_b128 v94, v[82:85]
	s_waitcnt vmcnt(1)
	ds_write_b128 v93, v[86:89] offset:10240
	s_waitcnt vmcnt(0)
	ds_write_b128 v94, v[98:101] offset:10240
	s_waitcnt lgkmcnt(0)
	s_barrier
	global_load_dwordx4 v[74:77], v[66:67], off offset:1472
	s_nop 0
	global_load_dwordx4 v[66:69], v[68:69], off offset:1472
	s_nop 0
	global_load_dwordx4 v[82:85], v[72:73], off offset:448
	s_nop 0
	global_load_dwordx4 v[70:73], v[70:71], off offset:448
	v_mfma_f32_32x32x16_bf16 v[48:63], v[128:131], v[120:123], v[48:63]
	v_mfma_f32_32x32x16_bf16 v[32:47], v[102:105], v[124:127], v[32:47]
	v_mfma_f32_32x32x16_bf16 v[16:31], v[106:109], v[124:127], v[16:31]
	v_mfma_f32_32x32x16_bf16 v[0:15], v[110:113], v[124:127], v[0:15]
	v_mfma_f32_32x32x16_bf16 v[48:63], v[132:135], v[124:127], v[48:63]
	ds_read_b128 v[86:89], v95 offset:12800
	ds_read_b128 v[98:101], v95 offset:15360
	ds_read_b128 v[102:105], v95 offset:17920
	ds_read_b128 v[106:109], v96
	ds_read_b128 v[110:113], v96 offset:32
	ds_read_b128 v[120:123], v95 offset:10240
	ds_read_b128 v[124:127], v95 offset:10272
	s_waitcnt lgkmcnt(3)
	v_mfma_f32_32x32x16_bf16 v[32:47], v[86:89], v[106:109], v[32:47]
	v_mfma_f32_32x32x16_bf16 v[16:31], v[98:101], v[106:109], v[16:31]
	v_mfma_f32_32x32x16_bf16 v[0:15], v[102:105], v[106:109], v[0:15]
	ds_read_b128 v[86:89], v95 offset:12832
	ds_read_b128 v[98:101], v95 offset:15392
	ds_read_b128 v[102:105], v95 offset:17952
	s_barrier
	s_waitcnt vmcnt(3)
	ds_write_b128 v93, v[74:77] offset:20480
	s_waitcnt vmcnt(2)
	ds_write_b128 v94, v[66:69] offset:20480
	s_waitcnt vmcnt(1)
	ds_write_b128 v93, v[82:85] offset:30720
	s_waitcnt vmcnt(0)
	ds_write_b128 v94, v[70:73] offset:30720
	s_waitcnt lgkmcnt(6)
	v_mfma_f32_32x32x16_bf16 v[32:47], v[86:89], v[110:113], v[32:47]
	s_waitcnt lgkmcnt(0)
	s_barrier
	v_mfma_f32_32x32x16_bf16 v[16:31], v[98:101], v[110:113], v[16:31]
	v_mfma_f32_32x32x16_bf16 v[0:15], v[102:105], v[110:113], v[0:15]
	ds_read_b128 v[66:69], v95 offset:33280
	ds_read_b128 v[70:73], v95 offset:35840
	ds_read_b128 v[74:77], v95 offset:38400
	ds_read_b128 v[82:85], v96 offset:20480
	ds_read_b128 v[86:89], v96 offset:20512
	ds_read_b128 v[98:101], v95 offset:30720
	ds_read_b128 v[102:105], v95 offset:30752
	v_mfma_f32_32x32x16_bf16 v[48:63], v[120:123], v[106:109], v[48:63]
	s_waitcnt lgkmcnt(3)
	v_mfma_f32_32x32x16_bf16 v[32:47], v[66:69], v[82:85], v[32:47]
	v_mfma_f32_32x32x16_bf16 v[16:31], v[70:73], v[82:85], v[16:31]
	v_mfma_f32_32x32x16_bf16 v[0:15], v[74:77], v[82:85], v[0:15]
	ds_read_b128 v[66:69], v95 offset:33312
	ds_read_b128 v[70:73], v95 offset:35872
	ds_read_b128 v[74:77], v95 offset:38432
	s_waitcnt lgkmcnt(0)
	s_barrier
	s_cmp_lg_u32 s10, 0
	s_cbranch_scc1 .Lkv_stg_end1
	s_barrier
; DI float bflo(unsigned u) { return __uint_as_float(u << 16); }
; DI float bfhi(unsigned u) { return __uint_as_float(u & 0xffff0000u); }
; DI void kv_tile(const Params& p, int mt, int hd, unsigned char* smem) {
;     ...
;     const int m = mw + r, s = sw + r;
;     const float rkv = rsqrtf(ssq[m] * (1.f / 256.f) + EPS);
;     float ss = 0.f;
; #pragma unroll
;     for (int j = 0; j < 4; ++j)
; #pragma unroll
;         for (int e = 0; e < 16; ++e) { const float v = acc[0][j][e] * rkv; acc[0][j][e] = v; ss += v * v; }
;     float x1[16], x2[16];
; #pragma unroll
;     for (int g = 0; g < 4; ++g) {
;         const u32x2 a = *(const u32x2*)(pa + (size_t)m * LDPA + C_KR + 8 * g + 4 * h);
;         const u32x2 c = *(const u32x2*)(pa + (size_t)m * LDPA + C_KR + 32 + 8 * g + 4 * h);
;         x1[4 * g] = bflo(a.x); x1[4 * g + 1] = bfhi(a.x); x1[4 * g + 2] = bflo(a.y); x1[4 * g + 3] = bfhi(a.y);
;         x2[4 * g] = bflo(c.x); x2[4 * g + 1] = bfhi(c.x); x2[4 * g + 2] = bflo(c.y); x2[4 * g + 3] = bfhi(c.y);
;     }
; #pragma unroll
;     for (int e = 0; e < 16; ++e) ss += x1[e] * x1[e] + x2[e] * x2[e];
;     ss += __shfl_xor(ss, 32);
;     const float rs = rsqrtf(ss * (1.f / 192.f) + EPS);
.Lkv_stg_end1:
	v_mfma_f32_32x32x16_bf16 v[48:63], v[124:127], v[110:113], v[48:63]
	v_lshlrev_b64 v[110:111], 2, v[64:65]
	v_mfma_f32_32x32x16_bf16 v[32:47], v[66:69], v[86:89], v[32:47]
	v_lshl_add_u64 v[66:67], s[76:77], 0, v[110:111]
	global_load_dword v65, v[66:67], off
	s_waitcnt vmcnt(0)
	v_fmamk_f32 v65, v65, 0x3b800000, v202
	v_cmp_gt_f32_e32 vcc, s53, v65
	v_mul_f32_e32 v66, 0x4b800000, v65
	v_mfma_f32_32x32x16_bf16 v[48:63], v[98:101], v[82:85], v[48:63]
	v_cndmask_b32_e32 v65, v65, v66, vcc
	v_rsq_f32_e32 v65, v65
	s_nop 0
	v_mul_f32_e32 v66, 0x45800000, v65
	v_cndmask_b32_e32 v176, v65, v66, vcc
	v_mov_b64_e32 v[66:67], s[8:9]
	v_mad_i64_i32 v[64:65], s[4:5], v64, s44, v[66:67]
	v_lshl_add_u64 v[64:65], v[64:65], 0, v[80:81]
	global_load_dwordx2 v[100:101], v[64:65], off offset:1536
	global_load_dwordx2 v[186:187], v[64:65], off offset:1600
	global_load_dwordx2 v[180:181], v[64:65], off offset:1552
	global_load_dwordx2 v[178:179], v[64:65], off offset:1616
	global_load_dwordx2 v[182:183], v[64:65], off offset:1568
	global_load_dwordx2 v[184:185], v[64:65], off offset:1632
	global_load_dwordx2 v[66:67], v[64:65], off offset:1584
	s_nop 0
	global_load_dwordx2 v[64:65], v[64:65], off offset:1648
	v_mfma_f32_32x32x16_bf16 v[48:63], v[102:105], v[86:89], v[48:63]
	v_readlane_b32 s4, v244, 31
	v_readlane_b32 s5, v244, 32
	s_movk_i32 s44, 0x180
	v_mul_f32_e64 v90, v32, v176
	v_mul_f32_e64 v91, v33, v176
	s_waitcnt vmcnt(3)
	v_and_b32_e32 v82, 0xffff0000, v183
	s_nop 4
	v_pk_mul_f32 v[108:109], v[48:49], v[176:177] op_sel_hi:[1,0]
	v_pk_mul_f32 v[106:107], v[50:51], v[176:177] op_sel_hi:[1,0]
	v_pk_mul_f32 v[146:147], v[108:109], v[108:109]
	v_pk_mul_f32 v[112:113], v[106:107], v[106:107]
	v_add_f32_e32 v119, v146, v147
	v_mfma_f32_32x32x16_bf16 v[0:15], v[74:77], v[86:89], v[0:15]
	s_waitcnt vmcnt(2)
	v_and_b32_e32 v76, 0xffff0000, v185
	v_lshlrev_b32_e32 v77, 16, v185
	v_mul_f32_e64 v104, v52, v176
	v_mul_f32_e64 v105, v53, v176
	v_add_f32_e32 v112, v112, v119
	v_lshlrev_b32_e32 v83, 16, v183
	v_pk_mul_f32 v[68:69], v[76:77], v[76:77]
	v_pk_mul_f32 v[148:149], v[104:105], v[104:105]
	v_mfma_f32_32x32x16_bf16 v[16:31], v[70:73], v[86:89], v[16:31]
	s_waitcnt vmcnt(0)
	v_and_b32_e32 v72, 0xffff0000, v64
	v_lshlrev_b32_e32 v73, 16, v64
	v_add_f32_e32 v112, v113, v112
	v_fma_f32 v84, v82, v82, v68
	v_fma_f32 v85, v83, v83, v69
	v_and_b32_e32 v74, 0xffff0000, v66
	v_lshlrev_b32_e32 v75, 16, v66
	v_pk_mul_f32 v[68:69], v[72:73], v[72:73]
	v_pk_mul_f32 v[102:103], v[54:55], v[176:177] op_sel_hi:[1,0]
	v_add_f32_e32 v112, v148, v112
	v_pk_fma_f32 v[86:87], v[74:75], v[74:75], v[68:69]
	v_and_b32_e32 v68, 0xffff0000, v65
	v_lshlrev_b32_e32 v69, 16, v65
	v_pk_mul_f32 v[114:115], v[102:103], v[102:103]
	v_add_f32_e32 v112, v149, v112
	v_and_b32_e32 v70, 0xffff0000, v67
	v_lshlrev_b32_e32 v71, 16, v67
	v_pk_mul_f32 v[64:65], v[68:69], v[68:69]
	v_pk_mul_f32 v[98:99], v[56:57], v[176:177] op_sel_hi:[1,0]
	v_add_f32_e32 v112, v114, v112
	v_pk_fma_f32 v[88:89], v[70:71], v[70:71], v[64:65]
	v_lshlrev_b64 v[64:65], 13, v[78:79]
	v_pk_mul_f32 v[150:151], v[98:99], v[98:99]
	v_add_f32_e32 v112, v115, v112
	v_or3_b32 v64, v97, v92, v64
	v_pk_mul_f32 v[96:97], v[58:59], v[176:177] op_sel_hi:[1,0]
	v_add_f32_e32 v112, v150, v112
	v_pk_mul_f32 v[120:121], v[96:97], v[96:97]
	v_add_f32_e32 v112, v151, v112
	v_pk_mul_f32 v[94:95], v[60:61], v[176:177] op_sel_hi:[1,0]
	v_add_f32_e32 v112, v120, v112
	v_pk_mul_f32 v[152:153], v[94:95], v[94:95]
	v_add_f32_e32 v112, v121, v112
	v_pk_mul_f32 v[92:93], v[62:63], v[176:177] op_sel_hi:[1,0]
	v_add_f32_e32 v112, v152, v112
	v_mov_b64_e32 v[66:67], s[4:5]
	v_pk_mul_f32 v[122:123], v[92:93], v[92:93]
	v_add_f32_e32 v112, v153, v112
	v_mad_u64_u32 v[78:79], s[4:5], v64, s44, v[66:67]
	v_add_f32_e32 v112, v122, v112
	v_mad_i32_i24 v79, v65, s44, v79
	v_pk_mul_f32 v[154:155], v[90:91], v[90:91]
	v_add_f32_e32 v112, v123, v112
	global_load_dwordx4 v[64:67], v116, s[58:59]
	v_lshl_add_u64 v[48:49], v[78:79], 0, v[80:81]
	v_pk_mul_f32 v[80:81], v[34:35], v[176:177] op_sel_hi:[1,0]
	v_add_f32_e32 v112, v154, v112
	v_pk_mul_f32 v[124:125], v[80:81], v[80:81]
	v_add_f32_e32 v112, v155, v112
	v_pk_mul_f32 v[78:79], v[36:37], v[176:177] op_sel_hi:[1,0]
	v_add_f32_e32 v112, v124, v112
	v_pk_mul_f32 v[156:157], v[78:79], v[78:79]
	v_add_f32_e32 v112, v125, v112
	v_pk_mul_f32 v[62:63], v[38:39], v[176:177] op_sel_hi:[1,0]
	v_add_f32_e32 v112, v156, v112
	v_pk_mul_f32 v[126:127], v[62:63], v[62:63]
	v_add_f32_e32 v112, v157, v112
	v_pk_mul_f32 v[60:61], v[40:41], v[176:177] op_sel_hi:[1,0]
	v_add_f32_e32 v112, v126, v112
	v_pk_mul_f32 v[158:159], v[60:61], v[60:61]
	v_add_f32_e32 v112, v127, v112
	v_pk_mul_f32 v[58:59], v[42:43], v[176:177] op_sel_hi:[1,0]
	v_add_f32_e32 v112, v158, v112
	v_pk_mul_f32 v[128:129], v[58:59], v[58:59]
	v_add_f32_e32 v112, v159, v112
	v_pk_mul_f32 v[56:57], v[44:45], v[176:177] op_sel_hi:[1,0]
	v_add_f32_e32 v112, v128, v112
	v_pk_mul_f32 v[160:161], v[56:57], v[56:57]
	v_add_f32_e32 v112, v129, v112
	v_pk_mul_f32 v[54:55], v[46:47], v[176:177] op_sel_hi:[1,0]
	v_add_f32_e32 v112, v160, v112
	v_pk_mul_f32 v[130:131], v[54:55], v[54:55]
	v_add_f32_e32 v112, v161, v112
	v_pk_mul_f32 v[52:53], v[16:17], v[176:177] op_sel_hi:[1,0]
	v_add_f32_e32 v112, v130, v112
	v_pk_mul_f32 v[162:163], v[52:53], v[52:53]
	v_add_f32_e32 v112, v131, v112
	v_pk_mul_f32 v[46:47], v[18:19], v[176:177] op_sel_hi:[1,0]
	v_add_f32_e32 v112, v162, v112
	v_pk_mul_f32 v[132:133], v[46:47], v[46:47]
	v_add_f32_e32 v112, v163, v112
	v_pk_mul_f32 v[42:43], v[20:21], v[176:177] op_sel_hi:[1,0]
	v_add_f32_e32 v112, v132, v112
; DI unsigned pk2(float a, float b) { f2_t v = {a, b}; bf2_t r = __builtin_convertvector(v, bf2_t); return __builtin_bit_cast(unsigned, r); }
; DI float bflo(unsigned u) { return __uint_as_float(u << 16); }
; DI float bfhi(unsigned u) { return __uint_as_float(u & 0xffff0000u); }
; DI void kv_tile(const Params& p, int mt, int hd, unsigned char* smem) {
;     ...
;     float ss = 0.f;
; #pragma unroll
;     for (int j = 0; j < 4; ++j)
; #pragma unroll
;         for (int e = 0; e < 16; ++e) { const float v = acc[0][j][e] * rkv; acc[0][j][e] = v; ss += v * v; }
;     float x1[16], x2[16];
; #pragma unroll
;     for (int g = 0; g < 4; ++g) {
;         const u32x2 a = *(const u32x2*)(pa + (size_t)m * LDPA + C_KR + 8 * g + 4 * h);
;         const u32x2 c = *(const u32x2*)(pa + (size_t)m * LDPA + C_KR + 32 + 8 * g + 4 * h);
;         x1[4 * g] = bflo(a.x); x1[4 * g + 1] = bfhi(a.x); x1[4 * g + 2] = bflo(a.y); x1[4 * g + 3] = bfhi(a.y);
;         x2[4 * g] = bflo(c.x); x2[4 * g + 1] = bfhi(c.x); x2[4 * g + 2] = bflo(c.y); x2[4 * g + 3] = bfhi(c.y);
;     }
; #pragma unroll
;     for (int e = 0; e < 16; ++e) ss += x1[e] * x1[e] + x2[e] * x2[e];
;     ss += __shfl_xor(ss, 32);
;     const float rs = rsqrtf(ss * (1.f / 192.f) + EPS);
;     bf16_t* krow = Kb + ((size_t)bh * SEQ_ + s) * 192;
; #pragma unroll
;     for (int j = 0; j < 4; ++j)
; #pragma unroll
;         for (int g = 0; g < 4; ++g) {
;             const int n = j * 32 + 8 * g + 4 * h;
;             const f32x4 gn = *(const f32x4*)(p.k_gain + n);
;             u32x2 o; o.x = pk2(acc[0][j][4 * g] * rs * gn.x, acc[0][j][4 * g + 1] * rs * gn.y);
;             o.y = pk2(acc[0][j][4 * g + 2] * rs * gn.z, acc[0][j][4 * g + 3] * rs * gn.w);
;             *(u32x2*)(krow + n) = o;
;         }
	v_pk_mul_f32 v[164:165], v[42:43], v[42:43]
	v_add_f32_e32 v112, v133, v112
	v_pk_mul_f32 v[40:41], v[22:23], v[176:177] op_sel_hi:[1,0]
	v_add_f32_e32 v112, v164, v112
	v_pk_mul_f32 v[134:135], v[40:41], v[40:41]
	v_add_f32_e32 v112, v165, v112
	v_pk_mul_f32 v[38:39], v[24:25], v[176:177] op_sel_hi:[1,0]
	v_add_f32_e32 v112, v134, v112
	v_pk_mul_f32 v[166:167], v[38:39], v[38:39]
	v_add_f32_e32 v112, v135, v112
	v_pk_mul_f32 v[36:37], v[26:27], v[176:177] op_sel_hi:[1,0]
	v_add_f32_e32 v112, v166, v112
	v_pk_mul_f32 v[136:137], v[36:37], v[36:37]
	v_add_f32_e32 v112, v167, v112
	v_pk_mul_f32 v[34:35], v[28:29], v[176:177] op_sel_hi:[1,0]
	v_add_f32_e32 v112, v136, v112
	v_pk_mul_f32 v[168:169], v[34:35], v[34:35]
	v_add_f32_e32 v112, v137, v112
	v_pk_mul_f32 v[32:33], v[30:31], v[176:177] op_sel_hi:[1,0]
	v_add_f32_e32 v112, v168, v112
	v_pk_mul_f32 v[138:139], v[32:33], v[32:33]
	v_add_f32_e32 v112, v169, v112
	v_pk_mul_f32 v[30:31], v[0:1], v[176:177] op_sel_hi:[1,0]
	v_add_f32_e32 v112, v138, v112
	v_pk_mul_f32 v[170:171], v[30:31], v[30:31]
	v_add_f32_e32 v112, v139, v112
	v_pk_mul_f32 v[28:29], v[2:3], v[176:177] op_sel_hi:[1,0]
	v_add_f32_e32 v112, v170, v112
	v_pk_mul_f32 v[140:141], v[28:29], v[28:29]
	v_add_f32_e32 v112, v171, v112
	v_pk_mul_f32 v[26:27], v[4:5], v[176:177] op_sel_hi:[1,0]
	v_add_f32_e32 v112, v140, v112
	v_pk_mul_f32 v[172:173], v[26:27], v[26:27]
	v_add_f32_e32 v112, v141, v112
	v_pk_mul_f32 v[24:25], v[6:7], v[176:177] op_sel_hi:[1,0]
	v_add_f32_e32 v112, v172, v112
	v_pk_mul_f32 v[0:1], v[24:25], v[24:25]
	v_add_f32_e32 v112, v173, v112
	v_pk_mul_f32 v[20:21], v[8:9], v[176:177] op_sel_hi:[1,0]
	v_add_f32_e32 v0, v0, v112
	v_pk_mul_f32 v[174:175], v[20:21], v[20:21]
	v_add_f32_e32 v0, v1, v0
	v_pk_mul_f32 v[18:19], v[10:11], v[176:177] op_sel_hi:[1,0]
	v_add_f32_e32 v0, v174, v0
	v_pk_mul_f32 v[142:143], v[18:19], v[18:19]
	v_add_f32_e32 v0, v175, v0
	v_pk_mul_f32 v[16:17], v[12:13], v[176:177] op_sel_hi:[1,0]
	v_add_f32_e32 v0, v142, v0
	v_pk_mul_f32 v[14:15], v[14:15], v[176:177] op_sel_hi:[1,0]
	v_pk_mul_f32 v[176:177], v[16:17], v[16:17]
	v_add_f32_e32 v0, v143, v0
	v_lshlrev_b32_e32 v44, 16, v187
	v_and_b32_e32 v45, 0xffff0000, v187
	v_add_f32_e32 v0, v176, v0
	v_pk_mul_f32 v[144:145], v[14:15], v[14:15]
	v_lshl_add_u64 v[10:11], s[42:43], 0, v[110:111]
	v_lshlrev_b32_e32 v50, 16, v101
	v_and_b32_e32 v51, 0xffff0000, v101
	v_pk_mul_f32 v[2:3], v[44:45], v[44:45]
	v_lshlrev_b32_e32 v110, 16, v100
	v_and_b32_e32 v111, 0xffff0000, v100
	v_lshlrev_b32_e32 v100, 16, v186
	v_and_b32_e32 v101, 0xffff0000, v186
	v_add_f32_e32 v0, v177, v0
	v_pk_fma_f32 v[188:189], v[50:51], v[50:51], v[2:3]
	v_pk_mul_f32 v[2:3], v[100:101], v[100:101]
	v_add_f32_e32 v0, v144, v0
	v_pk_fma_f32 v[186:187], v[110:111], v[110:111], v[2:3]
	v_add_f32_e32 v0, v145, v0
	v_lshlrev_b32_e32 v6, 16, v179
	v_and_b32_e32 v7, 0xffff0000, v179
	v_add_f32_e32 v0, v186, v0
	v_lshlrev_b32_e32 v8, 16, v181
	v_and_b32_e32 v9, 0xffff0000, v181
	v_pk_mul_f32 v[2:3], v[6:7], v[6:7]
	v_lshlrev_b32_e32 v12, 16, v178
	v_and_b32_e32 v13, 0xffff0000, v178
	v_add_f32_e32 v0, v187, v0
	v_pk_fma_f32 v[190:191], v[8:9], v[8:9], v[2:3]
	v_lshlrev_b32_e32 v22, 16, v180
	v_and_b32_e32 v23, 0xffff0000, v180
	v_pk_mul_f32 v[2:3], v[12:13], v[12:13]
	v_add_f32_e32 v0, v188, v0
	v_pk_fma_f32 v[178:179], v[22:23], v[22:23], v[2:3]
	v_add_f32_e32 v0, v189, v0
	v_add_f32_e32 v0, v178, v0
	v_lshlrev_b32_e32 v2, 16, v184
	v_and_b32_e32 v3, 0xffff0000, v184
	v_add_f32_e32 v0, v179, v0
	v_lshlrev_b32_e32 v4, 16, v182
	v_and_b32_e32 v5, 0xffff0000, v182
	v_pk_mul_f32 v[180:181], v[2:3], v[2:3]
	v_add_f32_e32 v0, v190, v0
	v_pk_fma_f32 v[180:181], v[4:5], v[4:5], v[180:181]
	v_add_f32_e32 v0, v191, v0
	v_add_f32_e32 v0, v180, v0
	v_add_f32_e32 v0, v181, v0
	v_add_f32_e32 v0, v85, v0
	v_add_f32_e32 v0, v84, v0
	v_add_f32_e32 v0, v87, v0
	v_add_f32_e32 v0, v86, v0
	v_add_f32_e32 v0, v89, v0
	v_add_f32_e32 v0, v88, v0
	ds_bpermute_b32 v1, v241, v0
	s_mov_b64 s[4:5], 0
	s_waitcnt lgkmcnt(0)
	v_add_f32_e32 v0, v0, v1
	v_fmamk_f32 v0, v0, 0x3baaaaab, v202
	v_cmp_gt_f32_e32 vcc, s53, v0
	v_mul_f32_e32 v1, 0x4b800000, v0
	s_nop 0
	v_cndmask_b32_e32 v0, v0, v1, vcc
	v_rsq_f32_e32 v0, v0
	s_nop 0
	v_mul_f32_e32 v1, 0x45800000, v0
	v_cndmask_b32_e32 v0, v0, v1, vcc
	v_pk_mul_f32 v[84:85], v[108:109], v[0:1] op_sel_hi:[1,0]
	v_pk_mul_f32 v[80:81], v[80:81], v[0:1] op_sel_hi:[1,0]
	s_waitcnt vmcnt(0)
	v_pk_mul_f32 v[64:65], v[64:65], v[84:85]
	v_pk_mul_f32 v[84:85], v[106:107], v[0:1] op_sel_hi:[1,0]
	v_cvt_pk_bf16_f32 v64, v64, v65
	v_pk_mul_f32 v[66:67], v[66:67], v[84:85]
	v_pk_mul_f32 v[84:85], v[104:105], v[0:1] op_sel_hi:[1,0]
	v_cvt_pk_bf16_f32 v65, v66, v67
	global_store_dwordx2 v[48:49], v[64:65], off
	global_load_dwordx4 v[64:67], v116, s[58:59] offset:32
	v_pk_mul_f32 v[78:79], v[78:79], v[0:1] op_sel_hi:[1,0]
	v_pk_mul_f32 v[62:63], v[62:63], v[0:1] op_sel_hi:[1,0]
	v_pk_mul_f32 v[60:61], v[60:61], v[0:1] op_sel_hi:[1,0]
	v_pk_mul_f32 v[58:59], v[58:59], v[0:1] op_sel_hi:[1,0]
	v_pk_mul_f32 v[56:57], v[56:57], v[0:1] op_sel_hi:[1,0]
	v_pk_mul_f32 v[54:55], v[54:55], v[0:1] op_sel_hi:[1,0]
	v_pk_mul_f32 v[52:53], v[52:53], v[0:1] op_sel_hi:[1,0]
	v_pk_mul_f32 v[46:47], v[46:47], v[0:1] op_sel_hi:[1,0]
	v_pk_mul_f32 v[42:43], v[42:43], v[0:1] op_sel_hi:[1,0]
	v_pk_mul_f32 v[40:41], v[40:41], v[0:1] op_sel_hi:[1,0]
	v_pk_mul_f32 v[38:39], v[38:39], v[0:1] op_sel_hi:[1,0]
	v_pk_mul_f32 v[36:37], v[36:37], v[0:1] op_sel_hi:[1,0]
	v_pk_mul_f32 v[34:35], v[34:35], v[0:1] op_sel_hi:[1,0]
	v_pk_mul_f32 v[32:33], v[32:33], v[0:1] op_sel_hi:[1,0]
	v_pk_mul_f32 v[30:31], v[30:31], v[0:1] op_sel_hi:[1,0]
	v_pk_mul_f32 v[28:29], v[28:29], v[0:1] op_sel_hi:[1,0]
	v_pk_mul_f32 v[26:27], v[26:27], v[0:1] op_sel_hi:[1,0]
	v_pk_mul_f32 v[24:25], v[24:25], v[0:1] op_sel_hi:[1,0]
	v_pk_mul_f32 v[20:21], v[20:21], v[0:1] op_sel_hi:[1,0]
	v_pk_mul_f32 v[18:19], v[18:19], v[0:1] op_sel_hi:[1,0]
	v_pk_mul_f32 v[16:17], v[16:17], v[0:1] op_sel_hi:[1,0]
	v_pk_mul_f32 v[14:15], v[14:15], v[0:1] op_sel_hi:[1,0]
	s_waitcnt vmcnt(0)
; DI unsigned pk2(float a, float b) { f2_t v = {a, b}; bf2_t r = __builtin_convertvector(v, bf2_t); return __builtin_bit_cast(unsigned, r); }
; DI void kv_tile(const Params& p, int mt, int hd, unsigned char* smem) {
;     ...
; #pragma unroll
;     for (int j = 0; j < 4; ++j)
; #pragma unroll
;         for (int g = 0; g < 4; ++g) {
;             const int n = j * 32 + 8 * g + 4 * h;
;             const f32x4 gn = *(const f32x4*)(p.k_gain + n);
;             u32x2 o; o.x = pk2(acc[0][j][4 * g] * rs * gn.x, acc[0][j][4 * g + 1] * rs * gn.y);
;             o.y = pk2(acc[0][j][4 * g + 2] * rs * gn.z, acc[0][j][4 * g + 3] * rs * gn.w);
;             *(u32x2*)(krow + n) = o;
;         }
;     const float posf = (float)p.pos[m];
;     const float* invf = (const float*)(p.ws + WS_CTRL + 256);
; #pragma unroll
;     for (int g = 0; g < 4; ++g) {
;         float o1[4], o2[4];
; #pragma unroll
;         for (int jj = 0; jj < 4; ++jj) {
;             const int i = 8 * g + 4 * h + jj;
;             float sn, cs; sincos_rev(posf * invf[i], sn, cs);
;             const float y1 = x1[4 * g + jj] * rs * p.k_gain[128 + i], y2 = x2[4 * g + jj] * rs * p.k_gain[160 + i];
;             o1[jj] = y1 * cs - y2 * sn; o2[jj] = y2 * cs + y1 * sn;
	v_pk_mul_f32 v[64:65], v[64:65], v[84:85]
	v_pk_mul_f32 v[84:85], v[102:103], v[0:1] op_sel_hi:[1,0]
	v_cvt_pk_bf16_f32 v64, v64, v65
	v_pk_mul_f32 v[66:67], v[66:67], v[84:85]
	v_pk_mul_f32 v[84:85], v[98:99], v[0:1] op_sel_hi:[1,0]
	v_cvt_pk_bf16_f32 v65, v66, v67
	global_store_dwordx2 v[48:49], v[64:65], off offset:16
	global_load_dwordx4 v[64:67], v116, s[58:59] offset:64
	s_waitcnt vmcnt(0)
	v_pk_mul_f32 v[64:65], v[64:65], v[84:85]
	v_pk_mul_f32 v[84:85], v[96:97], v[0:1] op_sel_hi:[1,0]
	v_cvt_pk_bf16_f32 v64, v64, v65
	v_pk_mul_f32 v[66:67], v[66:67], v[84:85]
	v_pk_mul_f32 v[84:85], v[94:95], v[0:1] op_sel_hi:[1,0]
	v_cvt_pk_bf16_f32 v65, v66, v67
	global_store_dwordx2 v[48:49], v[64:65], off offset:32
	global_load_dwordx4 v[64:67], v116, s[58:59] offset:96
	s_waitcnt vmcnt(0)
	v_pk_mul_f32 v[64:65], v[64:65], v[84:85]
	v_pk_mul_f32 v[84:85], v[92:93], v[0:1] op_sel_hi:[1,0]
	v_cvt_pk_bf16_f32 v64, v64, v65
	v_pk_mul_f32 v[66:67], v[66:67], v[84:85]
	v_pk_mul_f32 v[84:85], v[90:91], v[0:1] op_sel_hi:[1,0]
	v_cvt_pk_bf16_f32 v65, v66, v67
	global_store_dwordx2 v[48:49], v[64:65], off offset:48
	global_load_dwordx4 v[64:67], v116, s[58:59] offset:128
	s_waitcnt vmcnt(0)
	v_pk_mul_f32 v[64:65], v[64:65], v[84:85]
	v_pk_mul_f32 v[66:67], v[66:67], v[80:81]
	v_cvt_pk_bf16_f32 v64, v64, v65
	v_cvt_pk_bf16_f32 v65, v66, v67
	global_store_dwordx2 v[48:49], v[64:65], off offset:64
	global_load_dwordx4 v[64:67], v116, s[58:59] offset:160
	s_waitcnt vmcnt(0)
	v_pk_mul_f32 v[64:65], v[64:65], v[78:79]
	v_pk_mul_f32 v[62:63], v[66:67], v[62:63]
	v_cvt_pk_bf16_f32 v64, v64, v65
	v_cvt_pk_bf16_f32 v65, v62, v63
	global_store_dwordx2 v[48:49], v[64:65], off offset:80
	global_load_dwordx4 v[62:65], v116, s[58:59] offset:192
	s_waitcnt vmcnt(0)
	v_pk_mul_f32 v[60:61], v[62:63], v[60:61]
	v_pk_mul_f32 v[58:59], v[64:65], v[58:59]
	v_cvt_pk_bf16_f32 v60, v60, v61
	v_cvt_pk_bf16_f32 v61, v58, v59
	global_store_dwordx2 v[48:49], v[60:61], off offset:96
	global_load_dwordx4 v[58:61], v116, s[58:59] offset:224
	s_waitcnt vmcnt(0)
	v_pk_mul_f32 v[56:57], v[58:59], v[56:57]
	v_pk_mul_f32 v[54:55], v[60:61], v[54:55]
	v_cvt_pk_bf16_f32 v56, v56, v57
	v_cvt_pk_bf16_f32 v57, v54, v55
	global_store_dwordx2 v[48:49], v[56:57], off offset:112
	global_load_dwordx4 v[54:57], v116, s[58:59] offset:256
	s_waitcnt vmcnt(0)
	v_pk_mul_f32 v[52:53], v[54:55], v[52:53]
	v_pk_mul_f32 v[46:47], v[56:57], v[46:47]
	v_cvt_pk_bf16_f32 v52, v52, v53
	v_cvt_pk_bf16_f32 v53, v46, v47
	global_store_dwordx2 v[48:49], v[52:53], off offset:128
	global_load_dwordx4 v[52:55], v116, s[58:59] offset:288
	s_waitcnt vmcnt(0)
	v_pk_mul_f32 v[42:43], v[52:53], v[42:43]
	v_pk_mul_f32 v[40:41], v[54:55], v[40:41]
	v_cvt_pk_bf16_f32 v42, v42, v43
	v_cvt_pk_bf16_f32 v43, v40, v41
	global_store_dwordx2 v[48:49], v[42:43], off offset:144
	global_load_dwordx4 v[40:43], v116, s[58:59] offset:320
	s_waitcnt vmcnt(0)
	v_pk_mul_f32 v[38:39], v[40:41], v[38:39]
	v_pk_mul_f32 v[36:37], v[42:43], v[36:37]
	v_cvt_pk_bf16_f32 v38, v38, v39
	v_cvt_pk_bf16_f32 v39, v36, v37
	global_store_dwordx2 v[48:49], v[38:39], off offset:160
	global_load_dwordx4 v[36:39], v116, s[58:59] offset:352
	s_waitcnt vmcnt(0)
	v_pk_mul_f32 v[34:35], v[36:37], v[34:35]
	v_pk_mul_f32 v[32:33], v[38:39], v[32:33]
	v_cvt_pk_bf16_f32 v34, v34, v35
	v_cvt_pk_bf16_f32 v35, v32, v33
	global_store_dwordx2 v[48:49], v[34:35], off offset:176
	global_load_dwordx4 v[32:35], v116, s[58:59] offset:384
	s_waitcnt vmcnt(0)
	v_pk_mul_f32 v[30:31], v[32:33], v[30:31]
	v_pk_mul_f32 v[28:29], v[34:35], v[28:29]
	v_cvt_pk_bf16_f32 v30, v30, v31
	v_cvt_pk_bf16_f32 v31, v28, v29
	global_store_dwordx2 v[48:49], v[30:31], off offset:192
	global_load_dwordx4 v[28:31], v116, s[58:59] offset:416
	s_waitcnt vmcnt(0)
	v_pk_mul_f32 v[26:27], v[28:29], v[26:27]
	v_pk_mul_f32 v[24:25], v[30:31], v[24:25]
	v_cvt_pk_bf16_f32 v26, v26, v27
	v_cvt_pk_bf16_f32 v27, v24, v25
	global_store_dwordx2 v[48:49], v[26:27], off offset:208
	global_load_dwordx4 v[24:27], v116, s[58:59] offset:448
	s_waitcnt vmcnt(0)
	v_pk_mul_f32 v[20:21], v[24:25], v[20:21]
	v_pk_mul_f32 v[18:19], v[26:27], v[18:19]
	v_cvt_pk_bf16_f32 v20, v20, v21
	v_cvt_pk_bf16_f32 v21, v18, v19
	global_store_dwordx2 v[48:49], v[20:21], off offset:224
	global_load_dwordx4 v[18:21], v116, s[58:59] offset:480
	s_waitcnt vmcnt(0)
	v_pk_mul_f32 v[16:17], v[18:19], v[16:17]
	v_pk_mul_f32 v[14:15], v[20:21], v[14:15]
	v_cvt_pk_bf16_f32 v16, v16, v17
	v_cvt_pk_bf16_f32 v17, v14, v15
	global_store_dwordx2 v[48:49], v[16:17], off offset:240
	global_load_dword v1, v[10:11], off
	global_load_dwordx4 v[18:21], v116, s[58:59] offset:512
	s_waitcnt vmcnt(1)
	v_cvt_f32_i32_e32 v1, v1
	global_load_dwordx4 v[14:17], v116, s[72:73] offset:256
	v_pk_mul_f32 v[24:25], v[0:1], v[110:111] op_sel_hi:[0,1]
	s_waitcnt vmcnt(1)
	v_pk_mul_f32 v[18:19], v[18:19], v[24:25]
	global_load_dwordx4 v[24:27], v116, s[58:59] offset:640
	v_pk_mul_f32 v[30:31], v[0:1], v[100:101] op_sel_hi:[0,1]
	v_pk_mul_f32 v[22:23], v[0:1], v[22:23] op_sel_hi:[0,1]
	v_pk_mul_f32 v[12:13], v[0:1], v[12:13] op_sel_hi:[0,1]
	v_pk_mul_f32 v[6:7], v[0:1], v[6:7] op_sel_hi:[0,1]
	v_pk_mul_f32 v[8:9], v[0:1], v[8:9] op_sel_hi:[0,1]
	v_pk_mul_f32 v[4:5], v[0:1], v[4:5] op_sel_hi:[0,1]
	v_pk_mul_f32 v[2:3], v[0:1], v[2:3] op_sel_hi:[0,1]
	s_waitcnt vmcnt(1)
	v_mul_f32_e32 v10, v14, v1
	v_mul_f32_e32 v11, 0.15915494, v10
	v_fma_f32 v14, v10, 0.15915494, -v11
	v_fract_f32_e32 v11, v11
	v_fmac_f32_e32 v14, 0x31dc9c88, v10
	v_add_f32_e32 v11, v11, v14
	v_sin_f32_e32 v10, v11
	v_cos_f32_e32 v28, v11
	v_mul_f32_e32 v11, v15, v1
	v_mul_f32_e32 v14, 0.15915494, v11
	v_fma_f32 v15, v11, 0.15915494, -v14
	v_fract_f32_e32 v14, v14
	v_fmac_f32_e32 v15, 0x31dc9c88, v11
	v_add_f32_e32 v14, v14, v15
	v_sin_f32_e32 v11, v14
	v_cos_f32_e32 v29, v14
	s_waitcnt vmcnt(0)
; DI unsigned pk2(float a, float b) { f2_t v = {a, b}; bf2_t r = __builtin_convertvector(v, bf2_t); return __builtin_bit_cast(unsigned, r); }
; DI void kv_tile(const Params& p, int mt, int hd, unsigned char* smem) {
;     ...
;     const float posf = (float)p.pos[m];
;     const float* invf = (const float*)(p.ws + WS_CTRL + 256);
; #pragma unroll
;     for (int g = 0; g < 4; ++g) {
;         float o1[4], o2[4];
; #pragma unroll
;         for (int jj = 0; jj < 4; ++jj) {
;             const int i = 8 * g + 4 * h + jj;
;             float sn, cs; sincos_rev(posf * invf[i], sn, cs);
;             const float y1 = x1[4 * g + jj] * rs * p.k_gain[128 + i], y2 = x2[4 * g + jj] * rs * p.k_gain[160 + i];
;             o1[jj] = y1 * cs - y2 * sn; o2[jj] = y2 * cs + y1 * sn;
;         }
;         u32x2 a; a.x = pk2(o1[0], o1[1]); a.y = pk2(o1[2], o1[3]);
;         u32x2 c; c.x = pk2(o2[0], o2[1]); c.y = pk2(o2[2], o2[3]);
;         *(u32x2*)(krow + 128 + 8 * g + 4 * h) = a;
;         *(u32x2*)(krow + 160 + 8 * g + 4 * h) = c;
;     }
	v_pk_mul_f32 v[24:25], v[24:25], v[30:31]
	v_mul_f32_e32 v16, v16, v1
	v_pk_mul_f32 v[14:15], v[10:11], v[24:25]
	v_pk_mul_f32 v[10:11], v[10:11], v[18:19]
	v_pk_fma_f32 v[14:15], v[28:29], v[18:19], v[14:15] neg_lo:[0,0,1] neg_hi:[0,0,1]
	v_mul_f32_e32 v18, 0.15915494, v16
	v_fma_f32 v19, v16, 0.15915494, -v18
	v_pk_fma_f32 v[10:11], v[28:29], v[24:25], v[10:11]
	v_fract_f32_e32 v18, v18
	v_fmac_f32_e32 v19, 0x31dc9c88, v16
	v_pk_mul_f32 v[24:25], v[0:1], v[50:51] op_sel_hi:[0,1]
	v_mul_f32_e32 v17, v17, v1
	v_add_f32_e32 v16, v18, v19
	v_pk_mul_f32 v[20:21], v[20:21], v[24:25]
	v_pk_mul_f32 v[24:25], v[0:1], v[44:45] op_sel_hi:[0,1]
	v_mul_f32_e32 v19, 0.15915494, v17
	v_pk_mul_f32 v[24:25], v[26:27], v[24:25]
	v_fma_f32 v26, v17, 0.15915494, -v19
	v_fract_f32_e32 v19, v19
	v_fmac_f32_e32 v26, 0x31dc9c88, v17
	v_add_f32_e32 v17, v19, v26
	v_sin_f32_e32 v18, v16
	v_sin_f32_e32 v19, v17
	v_cos_f32_e32 v16, v16
	v_cos_f32_e32 v17, v17
	v_cvt_pk_bf16_f32 v14, v14, v15
	v_pk_mul_f32 v[26:27], v[18:19], v[24:25]
	v_pk_mul_f32 v[18:19], v[18:19], v[20:21]
	v_pk_fma_f32 v[26:27], v[16:17], v[20:21], v[26:27] neg_lo:[0,0,1] neg_hi:[0,0,1]
	v_pk_fma_f32 v[16:17], v[16:17], v[24:25], v[18:19]
	v_cvt_pk_bf16_f32 v15, v26, v27
	v_cvt_pk_bf16_f32 v10, v10, v11
	v_cvt_pk_bf16_f32 v11, v16, v17
	global_store_dwordx2 v[48:49], v[14:15], off offset:256
	global_store_dwordx2 v[48:49], v[10:11], off offset:320
	global_load_dwordx4 v[18:21], v116, s[58:59] offset:544
	s_waitcnt vmcnt(0)
	v_pk_mul_f32 v[18:19], v[18:19], v[22:23]
	global_load_dwordx4 v[14:17], v116, s[72:73] offset:288
	global_load_dwordx4 v[22:25], v116, s[58:59] offset:672
	v_pk_mul_f32 v[8:9], v[20:21], v[8:9]
	s_waitcnt vmcnt(1)
	v_mul_f32_e32 v10, v14, v1
	v_mul_f32_e32 v11, 0.15915494, v10
	v_fma_f32 v14, v10, 0.15915494, -v11
	v_fract_f32_e32 v11, v11
	v_fmac_f32_e32 v14, 0x31dc9c88, v10
	v_add_f32_e32 v11, v11, v14
	v_sin_f32_e32 v10, v11
	v_cos_f32_e32 v14, v11
	v_mul_f32_e32 v11, v15, v1
	s_waitcnt vmcnt(0)
	v_pk_mul_f32 v[22:23], v[22:23], v[12:13]
	v_mul_f32_e32 v12, 0.15915494, v11
	v_fma_f32 v13, v11, 0.15915494, -v12
	v_fract_f32_e32 v12, v12
	v_fmac_f32_e32 v13, 0x31dc9c88, v11
	v_add_f32_e32 v12, v12, v13
	v_sin_f32_e32 v11, v12
	v_cos_f32_e32 v15, v12
	v_pk_mul_f32 v[6:7], v[24:25], v[6:7]
	v_pk_mul_f32 v[12:13], v[10:11], v[22:23]
	v_pk_mul_f32 v[10:11], v[10:11], v[18:19]
	v_pk_fma_f32 v[12:13], v[14:15], v[18:19], v[12:13] neg_lo:[0,0,1] neg_hi:[0,0,1]
	v_pk_fma_f32 v[10:11], v[14:15], v[22:23], v[10:11]
	v_mul_f32_e32 v14, v16, v1
	v_mul_f32_e32 v15, 0.15915494, v14
	v_fma_f32 v16, v14, 0.15915494, -v15
	v_fract_f32_e32 v15, v15
	v_fmac_f32_e32 v16, 0x31dc9c88, v14
	v_add_f32_e32 v14, v15, v16
	v_mul_f32_e32 v15, v17, v1
	v_mul_f32_e32 v17, 0.15915494, v15
	v_fma_f32 v18, v15, 0.15915494, -v17
	v_fract_f32_e32 v17, v17
	v_fmac_f32_e32 v18, 0x31dc9c88, v15
	v_add_f32_e32 v15, v17, v18
	v_sin_f32_e32 v16, v14
	v_sin_f32_e32 v17, v15
	v_cos_f32_e32 v14, v14
	v_cos_f32_e32 v15, v15
	v_cvt_pk_bf16_f32 v10, v10, v11
	v_pk_mul_f32 v[18:19], v[16:17], v[6:7]
	s_nop 0
	v_pk_fma_f32 v[18:19], v[14:15], v[8:9], v[18:19] neg_lo:[0,0,1] neg_hi:[0,0,1]
	v_pk_mul_f32 v[8:9], v[16:17], v[8:9]
	s_nop 0
	v_pk_fma_f32 v[6:7], v[14:15], v[6:7], v[8:9]
	v_cvt_pk_bf16_f32 v8, v12, v13
	v_cvt_pk_bf16_f32 v9, v18, v19
	v_cvt_pk_bf16_f32 v11, v6, v7
	global_store_dwordx2 v[48:49], v[8:9], off offset:272
	global_store_dwordx2 v[48:49], v[10:11], off offset:336
	global_load_dwordx4 v[6:9], v116, s[72:73] offset:320
	s_waitcnt vmcnt(0)
	v_mul_f32_e32 v6, v6, v1
	v_mul_f32_e32 v10, 0.15915494, v6
	v_fma_f32 v11, v6, 0.15915494, -v10
	v_fract_f32_e32 v10, v10
	v_fmac_f32_e32 v11, 0x31dc9c88, v6
	v_add_f32_e32 v10, v10, v11
	v_sin_f32_e32 v6, v10
	v_cos_f32_e32 v18, v10
	global_load_dwordx4 v[10:13], v116, s[58:59] offset:576
	global_load_dwordx4 v[14:17], v116, s[58:59] offset:704
	s_waitcnt vmcnt(1)
	v_pk_mul_f32 v[10:11], v[10:11], v[4:5]
	v_mul_f32_e32 v4, v7, v1
	v_mul_f32_e32 v5, 0.15915494, v4
	v_fma_f32 v7, v4, 0.15915494, -v5
	v_fract_f32_e32 v5, v5
	v_fmac_f32_e32 v7, 0x31dc9c88, v4
	v_add_f32_e32 v4, v5, v7
	v_sin_f32_e32 v7, v4
	v_cos_f32_e32 v19, v4
	s_waitcnt vmcnt(0)
	v_pk_mul_f32 v[2:3], v[14:15], v[2:3]
	s_nop 0
	v_pk_mul_f32 v[4:5], v[6:7], v[2:3]
	v_pk_mul_f32 v[6:7], v[6:7], v[10:11]
	v_pk_fma_f32 v[4:5], v[18:19], v[10:11], v[4:5] neg_lo:[0,0,1] neg_hi:[0,0,1]
	v_pk_fma_f32 v[2:3], v[18:19], v[2:3], v[6:7]
	v_mul_f32_e32 v6, v8, v1
	v_mul_f32_e32 v7, 0.15915494, v6
	v_fma_f32 v8, v6, 0.15915494, -v7
	v_fract_f32_e32 v7, v7
	v_fmac_f32_e32 v8, 0x31dc9c88, v6
	v_add_f32_e32 v6, v7, v8
	v_mul_f32_e32 v7, v9, v1
	v_mul_f32_e32 v9, 0.15915494, v7
	v_fma_f32 v10, v7, 0.15915494, -v9
	v_fract_f32_e32 v9, v9
	v_fmac_f32_e32 v10, 0x31dc9c88, v7
	v_add_f32_e32 v7, v9, v10
	v_sin_f32_e32 v8, v6
	v_sin_f32_e32 v9, v7
	v_cos_f32_e32 v6, v6
	v_cos_f32_e32 v7, v7
	v_pk_mul_f32 v[10:11], v[0:1], v[82:83] op_sel_hi:[0,1]
	v_pk_mul_f32 v[10:11], v[12:13], v[10:11] op_sel:[0,1] op_sel_hi:[1,0]
	v_pk_mul_f32 v[12:13], v[0:1], v[76:77] op_sel_hi:[0,1]
	v_pk_mul_f32 v[12:13], v[16:17], v[12:13] op_sel:[0,1] op_sel_hi:[1,0]
	v_cvt_pk_bf16_f32 v4, v4, v5
	v_pk_mul_f32 v[14:15], v[8:9], v[12:13]
	v_pk_mul_f32 v[8:9], v[8:9], v[10:11]
	v_pk_fma_f32 v[14:15], v[6:7], v[10:11], v[14:15] neg_lo:[0,0,1] neg_hi:[0,0,1]
	v_pk_fma_f32 v[6:7], v[6:7], v[12:13], v[8:9]
	v_cvt_pk_bf16_f32 v5, v14, v15
	v_cvt_pk_bf16_f32 v2, v2, v3
	v_cvt_pk_bf16_f32 v3, v6, v7
	global_store_dwordx2 v[48:49], v[4:5], off offset:288
	global_store_dwordx2 v[48:49], v[2:3], off offset:352
	global_load_dwordx4 v[4:7], v116, s[72:73] offset:352
	s_waitcnt vmcnt(0)
; DI int fresh_tid(const Params& p) { int t = p.wave_u * 64 + (int)__builtin_amdgcn_mbcnt_hi(~0u, __builtin_amdgcn_mbcnt_lo(~0u, 0u)); asm volatile("" : "+v"(t)); return t; }
; template <int BM, int BN, int BK, int WAVES_M, int WAVES_N, int UNSWAP_FROM>
; DI void gemm_mainloop(const int tid, const bf16_t* __restrict__ A, int lda, const bf16_t* __restrict__ Bt, int ldb, int K, unsigned char* smem,
;                       f32x16 (&acc)[BM / WAVES_M / 32][BN / WAVES_N / 32]) {
;     ...
;     const int nk = K / BK;
;     ...
;     G_LOAD(0); G_STORE(0); __syncthreads();
; DI void q_tile(const Params& p, int mt, int hd, unsigned char* smem) {
;     ...
;     const int tid = fresh_tid(p), lane = tid & 63, wave = tid >> 6, r = lane & 31, h = lane >> 5;
;     f32x16 acc[1][6];
;     gemm_mainloop<128, 192, 32, 4, 1, 99>(tid, pa + (size_t)mt * 128 * LDPA, LDPA, wt + (size_t)hd * 192 * 512, 512, 512, smem, acc);
	v_mul_f32_e32 v2, v4, v1
	global_load_dwordx4 v[8:11], v116, s[58:59] offset:608
	global_load_dwordx4 v[12:15], v116, s[58:59] offset:736
	v_mul_f32_e32 v3, 0.15915494, v2
	v_fma_f32 v4, v2, 0.15915494, -v3
	v_fract_f32_e32 v3, v3
	v_fmac_f32_e32 v4, 0x31dc9c88, v2
	v_add_f32_e32 v3, v3, v4
	v_sin_f32_e32 v2, v3
	v_cos_f32_e32 v16, v3
	v_mul_f32_e32 v3, v5, v1
	v_mul_f32_e32 v4, 0.15915494, v3
	v_fma_f32 v5, v3, 0.15915494, -v4
	v_fract_f32_e32 v4, v4
	v_fmac_f32_e32 v5, 0x31dc9c88, v3
	v_add_f32_e32 v4, v4, v5
	v_sin_f32_e32 v3, v4
	v_cos_f32_e32 v17, v4
	v_pk_mul_f32 v[4:5], v[0:1], v[74:75] op_sel_hi:[0,1]
	v_mul_f32_e32 v6, v6, v1
	s_waitcnt vmcnt(1)
	v_pk_mul_f32 v[8:9], v[8:9], v[4:5] op_sel:[0,1] op_sel_hi:[1,0]
	v_pk_mul_f32 v[4:5], v[0:1], v[72:73] op_sel_hi:[0,1]
	s_waitcnt vmcnt(0)
	v_pk_mul_f32 v[12:13], v[12:13], v[4:5] op_sel:[0,1] op_sel_hi:[1,0]
	v_mul_f32_e32 v1, v7, v1
	v_pk_mul_f32 v[4:5], v[2:3], v[12:13]
	v_pk_mul_f32 v[2:3], v[2:3], v[8:9]
	v_pk_fma_f32 v[4:5], v[16:17], v[8:9], v[4:5] neg_lo:[0,0,1] neg_hi:[0,0,1]
	v_mul_f32_e32 v8, 0.15915494, v6
	v_fma_f32 v9, v6, 0.15915494, -v8
	v_fract_f32_e32 v8, v8
	v_fmac_f32_e32 v9, 0x31dc9c88, v6
	v_mul_f32_e32 v7, 0.15915494, v1
	v_add_f32_e32 v6, v8, v9
	v_fma_f32 v9, v1, 0.15915494, -v7
	v_fract_f32_e32 v7, v7
	v_fmac_f32_e32 v9, 0x31dc9c88, v1
	v_add_f32_e32 v1, v7, v9
	v_sin_f32_e32 v8, v6
	v_sin_f32_e32 v9, v1
	v_cos_f32_e32 v6, v6
	v_cos_f32_e32 v7, v1
	v_pk_fma_f32 v[2:3], v[16:17], v[12:13], v[2:3]
	v_pk_mul_f32 v[12:13], v[0:1], v[70:71] op_sel_hi:[0,1]
	v_pk_mul_f32 v[0:1], v[0:1], v[68:69] op_sel_hi:[0,1]
	v_pk_mul_f32 v[0:1], v[14:15], v[0:1] op_sel:[0,1] op_sel_hi:[1,0]
	v_pk_mul_f32 v[10:11], v[10:11], v[12:13] op_sel:[0,1] op_sel_hi:[1,0]
	v_pk_mul_f32 v[12:13], v[8:9], v[0:1]
	v_pk_mul_f32 v[8:9], v[8:9], v[10:11]
	v_pk_fma_f32 v[12:13], v[6:7], v[10:11], v[12:13] neg_lo:[0,0,1] neg_hi:[0,0,1]
	v_pk_fma_f32 v[0:1], v[6:7], v[0:1], v[8:9]
	v_cvt_pk_bf16_f32 v4, v4, v5
	v_cvt_pk_bf16_f32 v5, v12, v13
	v_cvt_pk_bf16_f32 v2, v2, v3
	v_cvt_pk_bf16_f32 v3, v0, v1
	global_store_dwordx2 v[48:49], v[4:5], off offset:304
	global_store_dwordx2 v[48:49], v[2:3], off offset:368
.LBB0_161:
	s_andn2_b64 vcc, exec, s[4:5]
	s_cbranch_vccnz .LBB0_163
	s_add_i32 s4, s51, 0xfffff000
	v_mov_b32_e32 v116, v227
	s_lshr_b32 s4, s4, 3
	s_mul_i32 s44, s4, 0x5c000
	v_ashrrev_i32_e32 v0, 31, v116
	v_lshrrev_b32_e32 v0, 30, v0
	s_lshl_b64 s[74:75], s[44:45], 1
	v_add_u32_e32 v0, v116, v0
	v_add_u32_e32 v6, 0x100, v116
	s_add_u32 s74, s8, s74
	v_ashrrev_i32_e32 v20, 2, v0
	v_and_b32_e32 v0, -4, v0
	v_ashrrev_i32_e32 v7, 31, v6
	v_add_u32_e32 v16, 0x200, v116
	s_addc_u32 s75, s9, s75
	s_mul_i32 s5, s15, 0x30000
	v_readlane_b32 s44, v244, 33
	v_sub_u32_e32 v26, v116, v0
	v_lshrrev_b32_e32 v7, 30, v7
	v_ashrrev_i32_e32 v17, 31, v16
	s_add_u32 s76, s44, s5
	v_readlane_b32 s5, v244, 34
	v_lshlrev_b32_e32 v2, 3, v26
	v_add_u32_e32 v7, v6, v7
	v_lshrrev_b32_e32 v17, 30, v17
	s_addc_u32 s77, s5, 0
	v_mov_b64_e32 v[4:5], s[74:75]
	s_movk_i32 s5, 0x1700
	v_ashrrev_i32_e32 v3, 31, v2
	v_ashrrev_i32_e32 v22, 2, v7
	v_and_b32_e32 v7, -4, v7
	v_add_u32_e32 v17, v16, v17
	v_ashrrev_i32_e32 v21, 31, v20
	v_mad_i64_i32 v[0:1], s[74:75], v20, s5, v[4:5]
	v_lshlrev_b64 v[8:9], 1, v[2:3]
	v_sub_u32_e32 v27, v6, v7
	v_ashrrev_i32_e32 v24, 2, v17
	v_and_b32_e32 v17, -4, v17
	v_lshl_add_u64 v[120:121], v[0:1], 0, v[8:9]
	v_lshlrev_b32_e32 v6, 3, v27
	v_lshlrev_b64 v[10:11], 10, v[20:21]
	v_sub_u32_e32 v21, v16, v17
	v_ashrrev_i32_e32 v25, 31, v24
	global_load_dwordx4 v[0:3], v[120:121], off
	v_ashrrev_i32_e32 v7, 31, v6
	v_lshlrev_b64 v[16:17], 10, v[24:25]
	v_lshlrev_b32_e32 v18, 3, v21
	v_ashrrev_i32_e32 v23, 31, v22
	v_mad_i64_i32 v[4:5], s[74:75], v22, s5, v[4:5]
	v_lshlrev_b64 v[12:13], 1, v[6:7]
	v_lshl_add_u64 v[16:17], s[76:77], 0, v[16:17]
	v_ashrrev_i32_e32 v19, 31, v18
	v_lshl_add_u64 v[122:123], v[4:5], 0, v[12:13]
	v_lshl_add_u64 v[10:11], s[76:77], 0, v[10:11]
	v_lshlrev_b64 v[14:15], 10, v[22:23]
	v_lshl_add_u64 v[128:129], v[18:19], 1, v[16:17]
	global_load_dwordx4 v[4:7], v[122:123], off
	v_lshl_add_u64 v[124:125], v[10:11], 0, v[8:9]
	v_lshl_add_u64 v[14:15], s[76:77], 0, v[14:15]
	global_load_dwordx4 v[16:19], v[128:129], off
	global_load_dwordx4 v[8:11], v[124:125], off
	v_lshl_add_u64 v[126:127], v[14:15], 0, v[12:13]
	global_load_dwordx4 v[12:15], v[126:127], off
	s_movk_i32 s5, 0x50
	v_lshlrev_b32_e32 v23, 4, v26
	v_mul_lo_u32 v20, v20, s5
	v_add3_u32 v130, v23, v20, s10
	v_and_b32_e32 v119, 31, v116
	s_mov_b32 s44, 0xfffffe0
	s_waitcnt vmcnt(4)
	ds_write_b128 v130, v[0:3]
	v_lshlrev_b32_e32 v0, 4, v27
	v_mul_lo_u32 v1, v22, s5
	v_add3_u32 v131, v0, v1, s10
	v_lshlrev_b32_e32 v0, 4, v21
	v_mul_lo_u32 v1, v24, s5
	v_add3_u32 v132, v0, v1, s10
	s_waitcnt vmcnt(3)
	ds_write_b128 v131, v[4:7]
	s_waitcnt vmcnt(1)
	ds_write_b128 v130, v[8:11] offset:10240
	s_waitcnt vmcnt(0)
	ds_write_b128 v131, v[12:15] offset:10240
	ds_write_b128 v132, v[16:19] offset:10240
	s_waitcnt lgkmcnt(0)
	s_barrier
	s_cmp_eq_u32 s10, 0
	s_cbranch_scc1 .Lq_stg_beg
	s_barrier
; #define MFMA(a, b, c) __builtin_amdgcn_mfma_f32_32x32x16_bf16((a), (b), (c), 0, 0, 0)
; template <int BM, int BN, int BK, int WAVES_M, int WAVES_N, int UNSWAP_FROM>
; DI void gemm_mainloop(const int tid, const bf16_t* __restrict__ A, int lda, const bf16_t* __restrict__ Bt, int ldb, int K, unsigned char* smem,
;                       f32x16 (&acc)[BM / WAVES_M / 32][BN / WAVES_N / 32]) {
;     ...
;     for (int kt = 0; kt < nk; ++kt) {
;         const int buf = kt & 1;
;         if (kt + 1 < nk) G_LOAD(kt + 1);
;         const unsigned char* sa_ = smem + buf * STAGE; const unsigned char* sb_ = sa_ + A_ST;
; #pragma unroll
;         for (int ks = 0; ks < BK / 16; ++ks) {
;             bf16x8 af[WM], bfr[WN];
; #pragma unroll
;             for (int i = 0; i < WM; ++i) af[i] = *(const bf16x8*)(sa_ + (((wm * WM + i) * 32 + r) * LS + ks * 16 + h * 8) * 2);
; #pragma unroll
;             for (int j = 0; j < WN; ++j) bfr[j] = *(const bf16x8*)(sb_ + (((wn * WN + j) * 32 + r) * LS + ks * 16 + h * 8) * 2);
; #pragma unroll
;             for (int i = 0; i < WM; ++i)
; #pragma unroll
;                 for (int j = 0; j < WN; ++j) {
;                     if (j < UNSWAP_FROM) acc[i][j] = MFMA(bfr[j], af[i], acc[i][j]);
;                     else acc[i][j] = MFMA(af[i], bfr[j], acc[i][j]);
;                 }
;         }
;         if (kt + 1 < nk) G_STORE(buf ^ 1);
;         __syncthreads();
.Lq_stg_beg:
	global_load_dwordx4 v[96:99], v[120:121], off offset:64
	global_load_dwordx4 v[100:103], v[122:123], off offset:64
	global_load_dwordx4 v[104:107], v[124:125], off offset:64
	global_load_dwordx4 v[108:111], v[126:127], off offset:64
	global_load_dwordx4 v[112:115], v[128:129], off offset:64
	v_lshrrev_b32_e32 v0, 1, v116
	v_and_or_b32 v1, v0, s44, v119
	v_and_b32_e32 v0, 16, v0
	v_mul_u32_u24_e32 v2, 0x50, v119
	v_mul_lo_u32 v1, v1, s5
	v_add3_u32 v133, v0, v2, s10
	v_add3_u32 v134, v1, v0, s10
	ds_read_b128 v[0:3], v133 offset:12800
	ds_read_b128 v[4:7], v133 offset:15360
	ds_read_b128 v[8:11], v133 offset:17920
	ds_read_b128 v[12:15], v133 offset:20480
	ds_read_b128 v[16:19], v133 offset:23040
	ds_read_b128 v[20:23], v134
	ds_read_b128 v[136:139], v134 offset:32
	ds_read_b128 v[24:27], v133 offset:10240
	ds_read_b128 v[140:143], v133 offset:10272
	ds_read_b128 v[144:147], v133 offset:12832
	ds_read_b128 v[148:151], v133 offset:15392
	ds_read_b128 v[152:155], v133 offset:17952
	ds_read_b128 v[156:159], v133 offset:20512
	ds_read_b128 v[160:163], v133 offset:23072
	s_waitcnt lgkmcnt(6)
	v_mfma_f32_32x32x16_bf16 v[80:95], v[24:27], v[20:23], 0
	s_barrier
	s_waitcnt vmcnt(4)
	ds_write_b128 v130, v[96:99] offset:25600
	s_waitcnt vmcnt(3)
	ds_write_b128 v131, v[100:103] offset:25600
	s_waitcnt vmcnt(2)
	ds_write_b128 v130, v[104:107] offset:35840
	s_waitcnt vmcnt(1)
	ds_write_b128 v131, v[108:111] offset:35840
	s_waitcnt vmcnt(0)
	ds_write_b128 v132, v[112:115] offset:35840
	s_waitcnt lgkmcnt(0)
	s_barrier
	global_load_dwordx4 v[96:99], v[120:121], off offset:128
	global_load_dwordx4 v[100:103], v[122:123], off offset:128
	global_load_dwordx4 v[104:107], v[124:125], off offset:128
	global_load_dwordx4 v[108:111], v[126:127], off offset:128
	global_load_dwordx4 v[112:115], v[128:129], off offset:128
	v_mfma_f32_32x32x16_bf16 v[64:79], v[0:3], v[20:23], 0
	v_mfma_f32_32x32x16_bf16 v[48:63], v[4:7], v[20:23], 0
	v_mfma_f32_32x32x16_bf16 v[32:47], v[8:11], v[20:23], 0
	v_mfma_f32_32x32x16_bf16 v[0:15], v[12:15], v[20:23], 0
	v_mfma_f32_32x32x16_bf16 v[16:31], v[16:19], v[20:23], 0
	v_mfma_f32_32x32x16_bf16 v[64:79], v[144:147], v[136:139], v[64:79]
	v_mfma_f32_32x32x16_bf16 v[48:63], v[148:151], v[136:139], v[48:63]
	v_mfma_f32_32x32x16_bf16 v[32:47], v[152:155], v[136:139], v[32:47]
	v_mfma_f32_32x32x16_bf16 v[0:15], v[156:159], v[136:139], v[0:15]
	v_mfma_f32_32x32x16_bf16 v[16:31], v[160:163], v[136:139], v[16:31]
	v_mfma_f32_32x32x16_bf16 v[80:95], v[140:143], v[136:139], v[80:95]
	ds_read_b128 v[136:139], v133 offset:38400
	ds_read_b128 v[140:143], v133 offset:40960
	ds_read_b128 v[144:147], v133 offset:43520
	ds_read_b128 v[148:151], v133 offset:46080
	ds_read_b128 v[152:155], v133 offset:48640
	ds_read_b128 v[156:159], v134 offset:25600
	ds_read_b128 v[160:163], v134 offset:25632
	ds_read_b128 v[164:167], v133 offset:35840
	ds_read_b128 v[168:171], v133 offset:35872
	s_waitcnt lgkmcnt(3)
	v_mfma_f32_32x32x16_bf16 v[64:79], v[136:139], v[156:159], v[64:79]
	v_mfma_f32_32x32x16_bf16 v[48:63], v[140:143], v[156:159], v[48:63]
	v_mfma_f32_32x32x16_bf16 v[32:47], v[144:147], v[156:159], v[32:47]
	v_mfma_f32_32x32x16_bf16 v[0:15], v[148:151], v[156:159], v[0:15]
	v_mfma_f32_32x32x16_bf16 v[16:31], v[152:155], v[156:159], v[16:31]
	ds_read_b128 v[136:139], v133 offset:38432
	ds_read_b128 v[140:143], v133 offset:40992
	ds_read_b128 v[144:147], v133 offset:43552
	ds_read_b128 v[148:151], v133 offset:46112
	ds_read_b128 v[152:155], v133 offset:48672
	s_barrier
	s_waitcnt vmcnt(4)
	ds_write_b128 v130, v[96:99]
	s_waitcnt vmcnt(3)
	ds_write_b128 v131, v[100:103]
	s_waitcnt vmcnt(2)
	ds_write_b128 v130, v[104:107] offset:10240
	s_waitcnt vmcnt(1)
	ds_write_b128 v131, v[108:111] offset:10240
	s_waitcnt vmcnt(0)
	ds_write_b128 v132, v[112:115] offset:10240
	s_waitcnt lgkmcnt(0)
	s_barrier
	s_mov_b64 s[100:101], 0x80
	s_movk_i32 s99, 6
.Lq_roll:
	global_load_dwordx4 v[96:99], v[120:121], off offset:192
	global_load_dwordx4 v[100:103], v[122:123], off offset:192
	global_load_dwordx4 v[104:107], v[124:125], off offset:192
	global_load_dwordx4 v[108:111], v[126:127], off offset:192
	global_load_dwordx4 v[112:115], v[128:129], off offset:192
	v_mfma_f32_32x32x16_bf16 v[80:95], v[164:167], v[156:159], v[80:95]
	v_mfma_f32_32x32x16_bf16 v[64:79], v[136:139], v[160:163], v[64:79]
	v_mfma_f32_32x32x16_bf16 v[48:63], v[140:143], v[160:163], v[48:63]
	v_mfma_f32_32x32x16_bf16 v[32:47], v[144:147], v[160:163], v[32:47]
	v_mfma_f32_32x32x16_bf16 v[0:15], v[148:151], v[160:163], v[0:15]
	v_mfma_f32_32x32x16_bf16 v[16:31], v[152:155], v[160:163], v[16:31]
	v_mfma_f32_32x32x16_bf16 v[80:95], v[168:171], v[160:163], v[80:95]
	ds_read_b128 v[136:139], v133 offset:12800
	ds_read_b128 v[140:143], v133 offset:15360
	ds_read_b128 v[144:147], v133 offset:17920
	ds_read_b128 v[148:151], v133 offset:20480
	ds_read_b128 v[152:155], v133 offset:23040
	ds_read_b128 v[156:159], v134
	ds_read_b128 v[160:163], v134 offset:32
	ds_read_b128 v[164:167], v133 offset:10240
	ds_read_b128 v[168:171], v133 offset:10272
	s_waitcnt lgkmcnt(3)
	v_mfma_f32_32x32x16_bf16 v[64:79], v[136:139], v[156:159], v[64:79]
	v_mfma_f32_32x32x16_bf16 v[48:63], v[140:143], v[156:159], v[48:63]
	v_mfma_f32_32x32x16_bf16 v[32:47], v[144:147], v[156:159], v[32:47]
	v_mfma_f32_32x32x16_bf16 v[0:15], v[148:151], v[156:159], v[0:15]
	v_mfma_f32_32x32x16_bf16 v[16:31], v[152:155], v[156:159], v[16:31]
	ds_read_b128 v[136:139], v133 offset:12832
	ds_read_b128 v[140:143], v133 offset:15392
	ds_read_b128 v[144:147], v133 offset:17952
	ds_read_b128 v[148:151], v133 offset:20512
	ds_read_b128 v[152:155], v133 offset:23072
	s_barrier
; #define MFMA(a, b, c) __builtin_amdgcn_mfma_f32_32x32x16_bf16((a), (b), (c), 0, 0, 0)
; template <int BM, int BN, int BK, int WAVES_M, int WAVES_N, int UNSWAP_FROM>
; DI void gemm_mainloop(const int tid, const bf16_t* __restrict__ A, int lda, const bf16_t* __restrict__ Bt, int ldb, int K, unsigned char* smem,
;                       f32x16 (&acc)[BM / WAVES_M / 32][BN / WAVES_N / 32]) {
;     ...
;     for (int kt = 0; kt < nk; ++kt) {
;         const int buf = kt & 1;
;         if (kt + 1 < nk) G_LOAD(kt + 1);
;         const unsigned char* sa_ = smem + buf * STAGE; const unsigned char* sb_ = sa_ + A_ST;
; #pragma unroll
;         for (int ks = 0; ks < BK / 16; ++ks) {
;             bf16x8 af[WM], bfr[WN];
; #pragma unroll
;             for (int i = 0; i < WM; ++i) af[i] = *(const bf16x8*)(sa_ + (((wm * WM + i) * 32 + r) * LS + ks * 16 + h * 8) * 2);
; #pragma unroll
;             for (int j = 0; j < WN; ++j) bfr[j] = *(const bf16x8*)(sb_ + (((wn * WN + j) * 32 + r) * LS + ks * 16 + h * 8) * 2);
; #pragma unroll
;             for (int i = 0; i < WM; ++i)
; #pragma unroll
;                 for (int j = 0; j < WN; ++j) {
;                     if (j < UNSWAP_FROM) acc[i][j] = MFMA(bfr[j], af[i], acc[i][j]);
;                     else acc[i][j] = MFMA(af[i], bfr[j], acc[i][j]);
;                 }
;         }
;         if (kt + 1 < nk) G_STORE(buf ^ 1);
;         __syncthreads();
	s_waitcnt vmcnt(4)
	ds_write_b128 v130, v[96:99] offset:25600
	s_waitcnt vmcnt(3)
	ds_write_b128 v131, v[100:103] offset:25600
	s_waitcnt vmcnt(2)
	ds_write_b128 v130, v[104:107] offset:35840
	s_waitcnt vmcnt(1)
	ds_write_b128 v131, v[108:111] offset:35840
	s_waitcnt vmcnt(0)
	ds_write_b128 v132, v[112:115] offset:35840
	s_waitcnt lgkmcnt(0)
	s_barrier
	global_load_dwordx4 v[96:99], v[120:121], off offset:256
	global_load_dwordx4 v[100:103], v[122:123], off offset:256
	global_load_dwordx4 v[104:107], v[124:125], off offset:256
	global_load_dwordx4 v[108:111], v[126:127], off offset:256
	global_load_dwordx4 v[112:115], v[128:129], off offset:256
	v_mfma_f32_32x32x16_bf16 v[80:95], v[164:167], v[156:159], v[80:95]
	v_mfma_f32_32x32x16_bf16 v[64:79], v[136:139], v[160:163], v[64:79]
	v_mfma_f32_32x32x16_bf16 v[48:63], v[140:143], v[160:163], v[48:63]
	v_mfma_f32_32x32x16_bf16 v[32:47], v[144:147], v[160:163], v[32:47]
	v_mfma_f32_32x32x16_bf16 v[0:15], v[148:151], v[160:163], v[0:15]
	v_mfma_f32_32x32x16_bf16 v[16:31], v[152:155], v[160:163], v[16:31]
	v_mfma_f32_32x32x16_bf16 v[80:95], v[168:171], v[160:163], v[80:95]
	ds_read_b128 v[136:139], v133 offset:38400
	ds_read_b128 v[140:143], v133 offset:40960
	ds_read_b128 v[144:147], v133 offset:43520
	ds_read_b128 v[148:151], v133 offset:46080
	ds_read_b128 v[152:155], v133 offset:48640
	ds_read_b128 v[156:159], v134 offset:25600
	ds_read_b128 v[160:163], v134 offset:25632
	ds_read_b128 v[164:167], v133 offset:35840
	ds_read_b128 v[168:171], v133 offset:35872
	s_waitcnt lgkmcnt(3)
	v_mfma_f32_32x32x16_bf16 v[64:79], v[136:139], v[156:159], v[64:79]
	v_mfma_f32_32x32x16_bf16 v[48:63], v[140:143], v[156:159], v[48:63]
	v_mfma_f32_32x32x16_bf16 v[32:47], v[144:147], v[156:159], v[32:47]
	v_mfma_f32_32x32x16_bf16 v[0:15], v[148:151], v[156:159], v[0:15]
	v_mfma_f32_32x32x16_bf16 v[16:31], v[152:155], v[156:159], v[16:31]
	ds_read_b128 v[136:139], v133 offset:38432
	ds_read_b128 v[140:143], v133 offset:40992
	ds_read_b128 v[144:147], v133 offset:43552
	ds_read_b128 v[148:151], v133 offset:46112
	ds_read_b128 v[152:155], v133 offset:48672
	s_barrier
	s_waitcnt vmcnt(4)
	ds_write_b128 v130, v[96:99]
	s_waitcnt vmcnt(3)
	ds_write_b128 v131, v[100:103]
	s_waitcnt vmcnt(2)
	ds_write_b128 v130, v[104:107] offset:10240
	s_waitcnt vmcnt(1)
	ds_write_b128 v131, v[108:111] offset:10240
	s_waitcnt vmcnt(0)
	ds_write_b128 v132, v[112:115] offset:10240
	s_waitcnt lgkmcnt(0)
	v_lshl_add_u64 v[120:121], v[120:121], 0, s[100:101]
	v_lshl_add_u64 v[122:123], v[122:123], 0, s[100:101]
	v_lshl_add_u64 v[124:125], v[124:125], 0, s[100:101]
	v_lshl_add_u64 v[126:127], v[126:127], 0, s[100:101]
	v_lshl_add_u64 v[128:129], v[128:129], 0, s[100:101]
	s_barrier
	s_add_i32 s99, s99, -1
	s_cmp_lg_u32 s99, 0
	s_cbranch_scc1 .Lq_roll
	s_mov_b32 s100, 0xfffffd00
	s_mov_b32 s101, -1
	v_lshl_add_u64 v[120:121], v[120:121], 0, s[100:101]
	v_lshl_add_u64 v[122:123], v[122:123], 0, s[100:101]
	v_lshl_add_u64 v[124:125], v[124:125], 0, s[100:101]
	v_lshl_add_u64 v[126:127], v[126:127], 0, s[100:101]
	v_lshl_add_u64 v[128:129], v[128:129], 0, s[100:101]
	global_load_dwordx4 v[96:99], v[120:121], off offset:960
	global_load_dwordx4 v[100:103], v[122:123], off offset:960
	global_load_dwordx4 v[104:107], v[124:125], off offset:960
	global_load_dwordx4 v[108:111], v[126:127], off offset:960
	global_load_dwordx4 v[112:115], v[128:129], off offset:960
	v_mfma_f32_32x32x16_bf16 v[80:95], v[164:167], v[156:159], v[80:95]
	v_mfma_f32_32x32x16_bf16 v[64:79], v[136:139], v[160:163], v[64:79]
	v_mfma_f32_32x32x16_bf16 v[48:63], v[140:143], v[160:163], v[48:63]
	v_mfma_f32_32x32x16_bf16 v[80:95], v[168:171], v[160:163], v[80:95]
	v_mfma_f32_32x32x16_bf16 v[32:47], v[144:147], v[160:163], v[32:47]
	v_mfma_f32_32x32x16_bf16 v[0:15], v[148:151], v[160:163], v[0:15]
	v_mfma_f32_32x32x16_bf16 v[16:31], v[152:155], v[160:163], v[16:31]
	ds_read_b128 v[120:123], v133 offset:12800
	ds_read_b128 v[124:127], v133 offset:15360
	ds_read_b128 v[136:139], v133 offset:17920
	ds_read_b128 v[140:143], v133 offset:20480
	ds_read_b128 v[144:147], v133 offset:23040
	ds_read_b128 v[148:151], v134
	ds_read_b128 v[152:155], v134 offset:32
	ds_read_b128 v[156:159], v133 offset:10240
	ds_read_b128 v[160:163], v133 offset:10272
	s_waitcnt lgkmcnt(3)
	v_mfma_f32_32x32x16_bf16 v[64:79], v[120:123], v[148:151], v[64:79]
	v_mfma_f32_32x32x16_bf16 v[48:63], v[124:127], v[148:151], v[48:63]
	s_waitcnt lgkmcnt(1)
	v_mfma_f32_32x32x16_bf16 v[80:95], v[156:159], v[148:151], v[80:95]
	v_mfma_f32_32x32x16_bf16 v[32:47], v[136:139], v[148:151], v[32:47]
	v_mfma_f32_32x32x16_bf16 v[0:15], v[140:143], v[148:151], v[0:15]
	v_mfma_f32_32x32x16_bf16 v[16:31], v[144:147], v[148:151], v[16:31]
	ds_read_b128 v[120:123], v133 offset:12832
	ds_read_b128 v[124:127], v133 offset:15392
	ds_read_b128 v[136:139], v133 offset:17952
	ds_read_b128 v[140:143], v133 offset:20512
	ds_read_b128 v[144:147], v133 offset:23072
	s_barrier
	s_waitcnt vmcnt(4)
	ds_write_b128 v130, v[96:99] offset:25600
	s_waitcnt vmcnt(3)
	ds_write_b128 v131, v[100:103] offset:25600
	s_waitcnt vmcnt(2)
	ds_write_b128 v130, v[104:107] offset:35840
	s_waitcnt vmcnt(1)
	ds_write_b128 v131, v[108:111] offset:35840
	s_waitcnt vmcnt(0)
	ds_write_b128 v132, v[112:115] offset:35840
	s_waitcnt lgkmcnt(0)
	s_barrier
	v_mfma_f32_32x32x16_bf16 v[64:79], v[120:123], v[152:155], v[64:79]
	v_mfma_f32_32x32x16_bf16 v[48:63], v[124:127], v[152:155], v[48:63]
	v_mfma_f32_32x32x16_bf16 v[80:95], v[160:163], v[152:155], v[80:95]
	v_mfma_f32_32x32x16_bf16 v[32:47], v[136:139], v[152:155], v[32:47]
	ds_read_b128 v[96:99], v133 offset:38400
	ds_read_b128 v[100:103], v133 offset:40960
	ds_read_b128 v[104:107], v133 offset:43520
	ds_read_b128 v[108:111], v133 offset:46080
	ds_read_b128 v[112:115], v133 offset:48640
	ds_read_b128 v[120:123], v134 offset:25600
	ds_read_b128 v[124:127], v134 offset:25632
	ds_read_b128 v[128:131], v133 offset:35840
	ds_read_b128 v[134:137], v133 offset:35872
	v_mfma_f32_32x32x16_bf16 v[0:15], v[140:143], v[152:155], v[0:15]
	v_mfma_f32_32x32x16_bf16 v[16:31], v[144:147], v[152:155], v[16:31]
	s_waitcnt lgkmcnt(3)
	v_mfma_f32_32x32x16_bf16 v[64:79], v[96:99], v[120:123], v[64:79]
	v_mfma_f32_32x32x16_bf16 v[48:63], v[100:103], v[120:123], v[48:63]
	s_waitcnt lgkmcnt(1)
	v_mfma_f32_32x32x16_bf16 v[80:95], v[128:131], v[120:123], v[80:95]
	v_mfma_f32_32x32x16_bf16 v[32:47], v[104:107], v[120:123], v[32:47]
	v_mfma_f32_32x32x16_bf16 v[0:15], v[108:111], v[120:123], v[0:15]
	v_mfma_f32_32x32x16_bf16 v[16:31], v[112:115], v[120:123], v[16:31]
	ds_read_b128 v[96:99], v133 offset:38432
	ds_read_b128 v[100:103], v133 offset:40992
	ds_read_b128 v[104:107], v133 offset:43552
	ds_read_b128 v[108:111], v133 offset:46112
	ds_read_b128 v[112:115], v133 offset:48672
	s_waitcnt lgkmcnt(0)
	s_barrier
	s_cmp_lg_u32 s10, 0
	s_cbranch_scc1 .Lq_stg_end
	s_barrier
; DI void q_tile(const Params& p, int mt, int hd, unsigned char* smem) {
;     ...
;     const int m = mt * 128 + wave * 32 + r;
;     const float rq = rsqrtf(ssq[m] * (1.f / 512.f) + EPS);
;     float ss = 0.f;
; #pragma unroll
;     for (int j = 0; j < 6; ++j)
; #pragma unroll
;         for (int e = 0; e < 16; ++e) { const float v = acc[0][j][e] * rq; acc[0][j][e] = v; ss += v * v; }
;     ss += __shfl_xor(ss, 32);
;     const float rs = rsqrtf(ss * (1.f / 192.f) + EPS) * QSCALE;
.Lq_stg_end:
	v_mfma_f32_32x32x16_bf16 v[64:79], v[96:99], v[124:127], v[64:79]
	v_ashrrev_i32_e32 v96, 1, v116
	v_and_b32_e32 v96, 0xffffffe0, v96
	v_mfma_f32_32x32x16_bf16 v[48:63], v[100:103], v[124:127], v[48:63]
	v_lshl_add_u32 v102, s4, 7, v96
	v_or_b32_e32 v100, v102, v119
	v_ashrrev_i32_e32 v101, 31, v100
	s_movk_i32 s4, 0x1fff
	v_mfma_f32_32x32x16_bf16 v[80:95], v[134:137], v[124:127], v[80:95]
	v_mfma_f32_32x32x16_bf16 v[32:47], v[104:107], v[124:127], v[32:47]
	v_mfma_f32_32x32x16_bf16 v[0:15], v[108:111], v[124:127], v[0:15]
	v_mfma_f32_32x32x16_bf16 v[16:31], v[112:115], v[124:127], v[16:31]
	v_lshlrev_b64 v[124:125], 2, v[100:101]
	v_lshl_add_u64 v[96:97], s[12:13], 0, v[124:125]
	global_load_dword v96, v[96:97], off
	s_waitcnt vmcnt(0)
	v_fmamk_f32 v96, v96, 0x3b000000, v202
	v_cmp_gt_f32_e32 vcc, s53, v96
	v_mul_f32_e32 v97, 0x4b800000, v96
	s_nop 0
	v_cndmask_b32_e32 v96, v96, v97, vcc
	v_rsq_f32_e32 v96, v96
	s_nop 0
	v_mul_f32_e32 v97, 0x45800000, v96
	v_cndmask_b32_e32 v122, v96, v97, vcc
	v_pk_mul_f32 v[98:99], v[28:29], v[122:123] op_sel_hi:[1,0]
	v_ashrrev_i32_e32 v28, 10, v102
	v_and_or_b32 v28, v28, -8, s15
	v_ashrrev_i32_e32 v29, 31, v28
	v_lshlrev_b64 v[28:29], 13, v[28:29]
	v_and_or_b32 v28, v100, s4, v28
	v_readlane_b32 s4, v244, 35
	v_readlane_b32 s5, v244, 36
	v_pk_mul_f32 v[96:97], v[30:31], v[122:123] op_sel_hi:[1,0]
	s_movk_i32 s15, 0x180
	v_mov_b64_e32 v[30:31], s[4:5]
	v_mad_u64_u32 v[100:101], s[4:5], v28, s15, v[30:31]
	v_lshrrev_b32_e32 v28, 3, v116
	v_and_b32_e32 v102, 4, v28
	v_pk_mul_f32 v[114:115], v[80:81], v[122:123] op_sel_hi:[1,0]
	v_mad_i32_i24 v101, v29, s15, v101
	v_pk_mul_f32 v[106:107], v[82:83], v[122:123] op_sel_hi:[1,0]
	v_pk_mul_f32 v[128:129], v[114:115], v[114:115]
	v_lshlrev_b32_e32 v116, 1, v102
	v_pk_mul_f32 v[126:127], v[106:107], v[106:107]
	v_lshl_add_u64 v[80:81], v[100:101], 0, v[116:117]
	v_add_f32_e32 v116, v128, v129
	v_pk_mul_f32 v[120:121], v[84:85], v[122:123] op_sel_hi:[1,0]
	v_add_f32_e32 v116, v126, v116
	v_pk_mul_f32 v[132:133], v[120:121], v[120:121]
	v_add_f32_e32 v116, v127, v116
	v_pk_mul_f32 v[112:113], v[86:87], v[122:123] op_sel_hi:[1,0]
	v_add_f32_e32 v116, v132, v116
	v_pk_mul_f32 v[130:131], v[112:113], v[112:113]
	v_add_f32_e32 v116, v133, v116
	v_pk_mul_f32 v[110:111], v[88:89], v[122:123] op_sel_hi:[1,0]
	v_add_f32_e32 v116, v130, v116
	v_pk_mul_f32 v[136:137], v[110:111], v[110:111]
	v_add_f32_e32 v116, v131, v116
	v_lshlrev_b32_e32 v119, 2, v102
	v_pk_mul_f32 v[102:103], v[90:91], v[122:123] op_sel_hi:[1,0]
	v_add_f32_e32 v116, v136, v116
	v_pk_mul_f32 v[134:135], v[102:103], v[102:103]
	v_add_f32_e32 v116, v137, v116
	v_pk_mul_f32 v[100:101], v[92:93], v[122:123] op_sel_hi:[1,0]
	v_add_f32_e32 v116, v134, v116
	v_pk_mul_f32 v[140:141], v[100:101], v[100:101]
	v_add_f32_e32 v116, v135, v116
	v_pk_mul_f32 v[94:95], v[94:95], v[122:123] op_sel_hi:[1,0]
	v_add_f32_e32 v116, v140, v116
	v_pk_mul_f32 v[138:139], v[94:95], v[94:95]
	v_add_f32_e32 v116, v141, v116
	v_pk_mul_f32 v[92:93], v[64:65], v[122:123] op_sel_hi:[1,0]
	v_add_f32_e32 v116, v138, v116
	v_pk_mul_f32 v[144:145], v[92:93], v[92:93]
	v_add_f32_e32 v116, v139, v116
	v_pk_mul_f32 v[90:91], v[66:67], v[122:123] op_sel_hi:[1,0]
	v_add_f32_e32 v116, v144, v116
	v_pk_mul_f32 v[142:143], v[90:91], v[90:91]
	v_add_f32_e32 v116, v145, v116
	v_pk_mul_f32 v[88:89], v[68:69], v[122:123] op_sel_hi:[1,0]
	v_add_f32_e32 v116, v142, v116
	v_pk_mul_f32 v[148:149], v[88:89], v[88:89]
	v_add_f32_e32 v116, v143, v116
	v_pk_mul_f32 v[86:87], v[70:71], v[122:123] op_sel_hi:[1,0]
	v_add_f32_e32 v116, v148, v116
	v_pk_mul_f32 v[146:147], v[86:87], v[86:87]
	v_add_f32_e32 v116, v149, v116
	v_pk_mul_f32 v[84:85], v[72:73], v[122:123] op_sel_hi:[1,0]
	v_add_f32_e32 v116, v146, v116
	v_pk_mul_f32 v[152:153], v[84:85], v[84:85]
	v_add_f32_e32 v116, v147, v116
	v_pk_mul_f32 v[82:83], v[74:75], v[122:123] op_sel_hi:[1,0]
	v_add_f32_e32 v116, v152, v116
	v_pk_mul_f32 v[150:151], v[82:83], v[82:83]
	v_add_f32_e32 v116, v153, v116
	v_pk_mul_f32 v[76:77], v[76:77], v[122:123] op_sel_hi:[1,0]
	v_add_f32_e32 v116, v150, v116
	v_pk_mul_f32 v[156:157], v[76:77], v[76:77]
	v_add_f32_e32 v116, v151, v116
	v_pk_mul_f32 v[78:79], v[78:79], v[122:123] op_sel_hi:[1,0]
	v_add_f32_e32 v116, v156, v116
	v_pk_mul_f32 v[154:155], v[78:79], v[78:79]
	v_add_f32_e32 v116, v157, v116
	v_pk_mul_f32 v[74:75], v[48:49], v[122:123] op_sel_hi:[1,0]
	v_add_f32_e32 v116, v154, v116
	v_pk_mul_f32 v[160:161], v[74:75], v[74:75]
	v_add_f32_e32 v116, v155, v116
	v_pk_mul_f32 v[72:73], v[50:51], v[122:123] op_sel_hi:[1,0]
	v_add_f32_e32 v116, v160, v116
	global_load_dwordx4 v[28:31], v119, s[56:57]
	v_pk_mul_f32 v[158:159], v[72:73], v[72:73]
	v_add_f32_e32 v116, v161, v116
	v_pk_mul_f32 v[70:71], v[52:53], v[122:123] op_sel_hi:[1,0]
	v_add_f32_e32 v116, v158, v116
	v_pk_mul_f32 v[164:165], v[70:71], v[70:71]
	v_add_f32_e32 v116, v159, v116
	v_pk_mul_f32 v[68:69], v[54:55], v[122:123] op_sel_hi:[1,0]
	v_add_f32_e32 v116, v164, v116
	v_pk_mul_f32 v[162:163], v[68:69], v[68:69]
	v_add_f32_e32 v116, v165, v116
	v_pk_mul_f32 v[66:67], v[56:57], v[122:123] op_sel_hi:[1,0]
	v_add_f32_e32 v116, v162, v116
	v_pk_mul_f32 v[168:169], v[66:67], v[66:67]
	v_add_f32_e32 v116, v163, v116
	v_pk_mul_f32 v[64:65], v[58:59], v[122:123] op_sel_hi:[1,0]
	v_add_f32_e32 v116, v168, v116
	v_pk_mul_f32 v[166:167], v[64:65], v[64:65]
	v_add_f32_e32 v116, v169, v116
	v_pk_mul_f32 v[60:61], v[60:61], v[122:123] op_sel_hi:[1,0]
	v_add_f32_e32 v116, v166, v116
	v_pk_mul_f32 v[172:173], v[60:61], v[60:61]
	v_add_f32_e32 v116, v167, v116
	v_pk_mul_f32 v[62:63], v[62:63], v[122:123] op_sel_hi:[1,0]
; DI unsigned pk2(float a, float b) { f2_t v = {a, b}; bf2_t r = __builtin_convertvector(v, bf2_t); return __builtin_bit_cast(unsigned, r); }
; DI void q_tile(const Params& p, int mt, int hd, unsigned char* smem) {
;     ...
; #pragma unroll
;     for (int j = 0; j < 6; ++j)
; #pragma unroll
;         for (int e = 0; e < 16; ++e) { const float v = acc[0][j][e] * rq; acc[0][j][e] = v; ss += v * v; }
;     ss += __shfl_xor(ss, 32);
;     const float rs = rsqrtf(ss * (1.f / 192.f) + EPS) * QSCALE;
;     const int bb = m >> 13, s = m & 8191;
;     bf16_t* qrow = Q + ((size_t)(bb * 8 + hd) * SEQ_ + s) * 192;
; #pragma unroll
;     for (int j = 0; j < 4; ++j)
; #pragma unroll
;         for (int g = 0; g < 4; ++g) {
;             const int n = j * 32 + 8 * g + 4 * h;
;             const f32x4 gn = *(const f32x4*)(p.q_gain + n);
;             u32x2 o; o.x = pk2(acc[0][j][4 * g] * rs * gn.x, acc[0][j][4 * g + 1] * rs * gn.y);
;             o.y = pk2(acc[0][j][4 * g + 2] * rs * gn.z, acc[0][j][4 * g + 3] * rs * gn.w);
;             *(u32x2*)(qrow + n) = o;
;         }
	v_add_f32_e32 v116, v172, v116
	v_pk_mul_f32 v[170:171], v[62:63], v[62:63]
	v_add_f32_e32 v116, v173, v116
	v_pk_mul_f32 v[58:59], v[32:33], v[122:123] op_sel_hi:[1,0]
	v_add_f32_e32 v116, v170, v116
	v_pk_mul_f32 v[176:177], v[58:59], v[58:59]
	v_add_f32_e32 v116, v171, v116
	v_pk_mul_f32 v[56:57], v[34:35], v[122:123] op_sel_hi:[1,0]
	v_add_f32_e32 v116, v176, v116
	v_pk_mul_f32 v[174:175], v[56:57], v[56:57]
	v_add_f32_e32 v116, v177, v116
	v_pk_mul_f32 v[54:55], v[36:37], v[122:123] op_sel_hi:[1,0]
	v_add_f32_e32 v116, v174, v116
	v_pk_mul_f32 v[180:181], v[54:55], v[54:55]
	v_add_f32_e32 v116, v175, v116
	v_pk_mul_f32 v[52:53], v[38:39], v[122:123] op_sel_hi:[1,0]
	v_add_f32_e32 v116, v180, v116
	v_pk_mul_f32 v[178:179], v[52:53], v[52:53]
	v_add_f32_e32 v116, v181, v116
	v_pk_mul_f32 v[50:51], v[40:41], v[122:123] op_sel_hi:[1,0]
	v_add_f32_e32 v116, v178, v116
	v_pk_mul_f32 v[184:185], v[50:51], v[50:51]
	v_add_f32_e32 v116, v179, v116
	v_pk_mul_f32 v[48:49], v[42:43], v[122:123] op_sel_hi:[1,0]
	v_add_f32_e32 v116, v184, v116
	v_pk_mul_f32 v[182:183], v[48:49], v[48:49]
	v_add_f32_e32 v116, v185, v116
	v_pk_mul_f32 v[44:45], v[44:45], v[122:123] op_sel_hi:[1,0]
	v_add_f32_e32 v116, v182, v116
	v_pk_mul_f32 v[188:189], v[44:45], v[44:45]
	v_add_f32_e32 v116, v183, v116
	v_pk_mul_f32 v[46:47], v[46:47], v[122:123] op_sel_hi:[1,0]
	v_add_f32_e32 v116, v188, v116
	v_pk_mul_f32 v[186:187], v[46:47], v[46:47]
	v_add_f32_e32 v116, v189, v116
	v_pk_mul_f32 v[42:43], v[0:1], v[122:123] op_sel_hi:[1,0]
	v_add_f32_e32 v116, v186, v116
	v_pk_mul_f32 v[190:191], v[42:43], v[42:43]
	v_add_f32_e32 v116, v187, v116
	v_pk_mul_f32 v[36:37], v[2:3], v[122:123] op_sel_hi:[1,0]
	v_add_f32_e32 v116, v190, v116
	v_pk_mul_f32 v[2:3], v[36:37], v[36:37]
	v_add_f32_e32 v116, v191, v116
	v_pk_mul_f32 v[34:35], v[18:19], v[122:123] op_sel_hi:[1,0]
	v_pk_mul_f32 v[18:19], v[22:23], v[122:123] op_sel_hi:[1,0]
	v_pk_mul_f32 v[22:23], v[4:5], v[122:123] op_sel_hi:[1,0]
	v_add_f32_e32 v2, v2, v116
	v_pk_mul_f32 v[214:215], v[22:23], v[22:23]
	v_add_f32_e32 v2, v3, v2
	v_pk_mul_f32 v[32:33], v[6:7], v[122:123] op_sel_hi:[1,0]
	v_add_f32_e32 v2, v214, v2
	v_pk_mul_f32 v[210:211], v[32:33], v[32:33]
	v_add_f32_e32 v2, v215, v2
	v_pk_mul_f32 v[38:39], v[16:17], v[122:123] op_sel_hi:[1,0]
	v_pk_mul_f32 v[16:17], v[8:9], v[122:123] op_sel_hi:[1,0]
	v_add_f32_e32 v2, v210, v2
	v_pk_mul_f32 v[220:221], v[16:17], v[16:17]
	v_add_f32_e32 v2, v211, v2
	v_pk_mul_f32 v[10:11], v[10:11], v[122:123] op_sel_hi:[1,0]
	v_add_f32_e32 v2, v220, v2
	v_pk_mul_f32 v[218:219], v[10:11], v[10:11]
	v_add_f32_e32 v2, v221, v2
	v_pk_mul_f32 v[4:5], v[12:13], v[122:123] op_sel_hi:[1,0]
	v_add_f32_e32 v2, v218, v2
	v_pk_mul_f32 v[12:13], v[4:5], v[4:5]
	v_add_f32_e32 v2, v219, v2
	v_pk_mul_f32 v[0:1], v[14:15], v[122:123] op_sel_hi:[1,0]
	v_add_f32_e32 v2, v12, v2
	v_pk_mul_f32 v[14:15], v[0:1], v[0:1]
	v_add_f32_e32 v2, v13, v2
	v_add_f32_e32 v2, v14, v2
	v_pk_mul_f32 v[208:209], v[38:39], v[38:39]
	v_add_f32_e32 v2, v15, v2
	v_add_f32_e32 v2, v208, v2
	v_lshl_add_u64 v[40:41], s[42:43], 0, v[124:125]
	v_pk_mul_f32 v[124:125], v[34:35], v[34:35]
	v_add_f32_e32 v2, v209, v2
	v_pk_mul_f32 v[20:21], v[20:21], v[122:123] op_sel_hi:[1,0]
	v_add_f32_e32 v2, v124, v2
	v_pk_mul_f32 v[216:217], v[20:21], v[20:21]
	v_add_f32_e32 v2, v125, v2
	v_add_f32_e32 v2, v216, v2
	v_pk_mul_f32 v[212:213], v[18:19], v[18:19]
	v_add_f32_e32 v2, v217, v2
	v_pk_mul_f32 v[8:9], v[24:25], v[122:123] op_sel_hi:[1,0]
	v_add_f32_e32 v2, v212, v2
	v_pk_mul_f32 v[24:25], v[8:9], v[8:9]
	v_add_f32_e32 v2, v213, v2
	v_pk_mul_f32 v[6:7], v[26:27], v[122:123] op_sel_hi:[1,0]
	v_add_f32_e32 v2, v24, v2
	v_pk_mul_f32 v[26:27], v[6:7], v[6:7]
	v_add_f32_e32 v2, v25, v2
	v_add_f32_e32 v2, v26, v2
	v_pk_mul_f32 v[104:105], v[98:99], v[98:99]
	v_add_f32_e32 v2, v27, v2
	v_add_f32_e32 v2, v104, v2
	v_pk_mul_f32 v[108:109], v[96:97], v[96:97]
	v_add_f32_e32 v2, v105, v2
	v_add_f32_e32 v2, v108, v2
	v_add_f32_e32 v2, v109, v2
	ds_bpermute_b32 v3, v241, v2
	s_waitcnt lgkmcnt(0)
	v_add_f32_e32 v2, v2, v3
	v_fmamk_f32 v2, v2, 0x3baaaaab, v202
	v_cmp_gt_f32_e32 vcc, s53, v2
	v_mul_f32_e32 v3, 0x4b800000, v2
	s_nop 0
	v_cndmask_b32_e32 v2, v2, v3, vcc
	v_rsq_f32_e32 v2, v2
	s_nop 0
	v_mul_f32_e32 v3, 0x45800000, v2
	v_cndmask_b32_e32 v2, v2, v3, vcc
	v_mul_f32_e32 v2, 0x3dd53b94, v2
	v_pk_mul_f32 v[12:13], v[114:115], v[2:3] op_sel_hi:[1,0]
	v_pk_mul_f32 v[14:15], v[106:107], v[2:3] op_sel_hi:[1,0]
	s_waitcnt vmcnt(0)
	v_pk_mul_f32 v[12:13], v[28:29], v[12:13]
	v_pk_mul_f32 v[14:15], v[30:31], v[14:15]
	v_cvt_pk_bf16_f32 v12, v12, v13
	v_cvt_pk_bf16_f32 v13, v14, v15
	global_store_dwordx2 v[80:81], v[12:13], off
	global_load_dwordx4 v[12:15], v119, s[56:57] offset:32
	v_pk_mul_f32 v[24:25], v[120:121], v[2:3] op_sel_hi:[1,0]
	s_waitcnt vmcnt(0)
	v_pk_mul_f32 v[12:13], v[12:13], v[24:25]
	v_pk_mul_f32 v[24:25], v[112:113], v[2:3] op_sel_hi:[1,0]
	v_cvt_pk_bf16_f32 v12, v12, v13
	v_pk_mul_f32 v[14:15], v[14:15], v[24:25]
	v_pk_mul_f32 v[24:25], v[110:111], v[2:3] op_sel_hi:[1,0]
	v_cvt_pk_bf16_f32 v13, v14, v15
	global_store_dwordx2 v[80:81], v[12:13], off offset:16
	global_load_dwordx4 v[12:15], v119, s[56:57] offset:64
	s_waitcnt vmcnt(0)
	v_pk_mul_f32 v[12:13], v[12:13], v[24:25]
	v_pk_mul_f32 v[24:25], v[102:103], v[2:3] op_sel_hi:[1,0]
	v_cvt_pk_bf16_f32 v12, v12, v13
	v_pk_mul_f32 v[14:15], v[14:15], v[24:25]
	v_pk_mul_f32 v[24:25], v[100:101], v[2:3] op_sel_hi:[1,0]
	v_cvt_pk_bf16_f32 v13, v14, v15
	global_store_dwordx2 v[80:81], v[12:13], off offset:32
	global_load_dwordx4 v[12:15], v119, s[56:57] offset:96
	s_waitcnt vmcnt(0)
; DI unsigned pk2(float a, float b) { f2_t v = {a, b}; bf2_t r = __builtin_convertvector(v, bf2_t); return __builtin_bit_cast(unsigned, r); }
; DI void q_tile(const Params& p, int mt, int hd, unsigned char* smem) {
;     ...
; #pragma unroll
;     for (int j = 0; j < 4; ++j)
; #pragma unroll
;         for (int g = 0; g < 4; ++g) {
;             const int n = j * 32 + 8 * g + 4 * h;
;             const f32x4 gn = *(const f32x4*)(p.q_gain + n);
;             u32x2 o; o.x = pk2(acc[0][j][4 * g] * rs * gn.x, acc[0][j][4 * g + 1] * rs * gn.y);
;             o.y = pk2(acc[0][j][4 * g + 2] * rs * gn.z, acc[0][j][4 * g + 3] * rs * gn.w);
;             *(u32x2*)(qrow + n) = o;
;         }
;     const float posf = (float)p.pos[m];
;     const float* invf = (const float*)(p.ws + WS_CTRL + 256);
; #pragma unroll
;     for (int g = 0; g < 4; ++g) {
;         float o1[4], o2[4];
; #pragma unroll
;         for (int jj = 0; jj < 4; ++jj) {
;             const int i = 8 * g + 4 * h + jj;
;             float sn, cs; sincos_rev(posf * invf[i], sn, cs);
;             const float x1 = acc[0][4][4 * g + jj] * rs * p.q_gain[128 + i], x2 = acc[0][5][4 * g + jj] * rs * p.q_gain[160 + i];
	v_pk_mul_f32 v[12:13], v[12:13], v[24:25]
	v_pk_mul_f32 v[24:25], v[94:95], v[2:3] op_sel_hi:[1,0]
	v_cvt_pk_bf16_f32 v12, v12, v13
	v_pk_mul_f32 v[14:15], v[14:15], v[24:25]
	v_pk_mul_f32 v[24:25], v[92:93], v[2:3] op_sel_hi:[1,0]
	v_cvt_pk_bf16_f32 v13, v14, v15
	global_store_dwordx2 v[80:81], v[12:13], off offset:48
	global_load_dwordx4 v[12:15], v119, s[56:57] offset:128
	s_waitcnt vmcnt(0)
	v_pk_mul_f32 v[12:13], v[12:13], v[24:25]
	v_pk_mul_f32 v[24:25], v[90:91], v[2:3] op_sel_hi:[1,0]
	v_cvt_pk_bf16_f32 v12, v12, v13
	v_pk_mul_f32 v[14:15], v[14:15], v[24:25]
	v_pk_mul_f32 v[24:25], v[88:89], v[2:3] op_sel_hi:[1,0]
	v_cvt_pk_bf16_f32 v13, v14, v15
	global_store_dwordx2 v[80:81], v[12:13], off offset:64
	global_load_dwordx4 v[12:15], v119, s[56:57] offset:160
	s_waitcnt vmcnt(0)
	v_pk_mul_f32 v[12:13], v[12:13], v[24:25]
	v_pk_mul_f32 v[24:25], v[86:87], v[2:3] op_sel_hi:[1,0]
	v_cvt_pk_bf16_f32 v12, v12, v13
	v_pk_mul_f32 v[14:15], v[14:15], v[24:25]
	v_pk_mul_f32 v[24:25], v[84:85], v[2:3] op_sel_hi:[1,0]
	v_cvt_pk_bf16_f32 v13, v14, v15
	global_store_dwordx2 v[80:81], v[12:13], off offset:80
	global_load_dwordx4 v[12:15], v119, s[56:57] offset:192
	s_waitcnt vmcnt(0)
	v_pk_mul_f32 v[12:13], v[12:13], v[24:25]
	v_pk_mul_f32 v[24:25], v[82:83], v[2:3] op_sel_hi:[1,0]
	v_cvt_pk_bf16_f32 v12, v12, v13
	v_pk_mul_f32 v[14:15], v[14:15], v[24:25]
	v_pk_mul_f32 v[24:25], v[76:77], v[2:3] op_sel_hi:[1,0]
	v_cvt_pk_bf16_f32 v13, v14, v15
	global_store_dwordx2 v[80:81], v[12:13], off offset:96
	global_load_dwordx4 v[12:15], v119, s[56:57] offset:224
	s_waitcnt vmcnt(0)
	v_pk_mul_f32 v[12:13], v[12:13], v[24:25]
	v_pk_mul_f32 v[24:25], v[78:79], v[2:3] op_sel_hi:[1,0]
	v_cvt_pk_bf16_f32 v12, v12, v13
	v_pk_mul_f32 v[14:15], v[14:15], v[24:25]
	v_pk_mul_f32 v[24:25], v[74:75], v[2:3] op_sel_hi:[1,0]
	v_cvt_pk_bf16_f32 v13, v14, v15
	global_store_dwordx2 v[80:81], v[12:13], off offset:112
	global_load_dwordx4 v[12:15], v119, s[56:57] offset:256
	s_waitcnt vmcnt(0)
	v_pk_mul_f32 v[12:13], v[12:13], v[24:25]
	v_pk_mul_f32 v[24:25], v[72:73], v[2:3] op_sel_hi:[1,0]
	v_cvt_pk_bf16_f32 v12, v12, v13
	v_pk_mul_f32 v[14:15], v[14:15], v[24:25]
	v_pk_mul_f32 v[24:25], v[70:71], v[2:3] op_sel_hi:[1,0]
	v_cvt_pk_bf16_f32 v13, v14, v15
	global_store_dwordx2 v[80:81], v[12:13], off offset:128
	global_load_dwordx4 v[12:15], v119, s[56:57] offset:288
	s_waitcnt vmcnt(0)
	v_pk_mul_f32 v[12:13], v[12:13], v[24:25]
	v_pk_mul_f32 v[24:25], v[68:69], v[2:3] op_sel_hi:[1,0]
	v_cvt_pk_bf16_f32 v12, v12, v13
	v_pk_mul_f32 v[14:15], v[14:15], v[24:25]
	v_pk_mul_f32 v[24:25], v[66:67], v[2:3] op_sel_hi:[1,0]
	v_cvt_pk_bf16_f32 v13, v14, v15
	global_store_dwordx2 v[80:81], v[12:13], off offset:144
	global_load_dwordx4 v[12:15], v119, s[56:57] offset:320
	s_waitcnt vmcnt(0)
	v_pk_mul_f32 v[12:13], v[12:13], v[24:25]
	v_pk_mul_f32 v[24:25], v[64:65], v[2:3] op_sel_hi:[1,0]
	v_cvt_pk_bf16_f32 v12, v12, v13
	v_pk_mul_f32 v[14:15], v[14:15], v[24:25]
	v_pk_mul_f32 v[24:25], v[60:61], v[2:3] op_sel_hi:[1,0]
	v_cvt_pk_bf16_f32 v13, v14, v15
	global_store_dwordx2 v[80:81], v[12:13], off offset:160
	global_load_dwordx4 v[12:15], v119, s[56:57] offset:352
	s_waitcnt vmcnt(0)
	v_pk_mul_f32 v[12:13], v[12:13], v[24:25]
	v_pk_mul_f32 v[24:25], v[62:63], v[2:3] op_sel_hi:[1,0]
	v_cvt_pk_bf16_f32 v12, v12, v13
	v_pk_mul_f32 v[14:15], v[14:15], v[24:25]
	v_pk_mul_f32 v[24:25], v[58:59], v[2:3] op_sel_hi:[1,0]
	v_cvt_pk_bf16_f32 v13, v14, v15
	global_store_dwordx2 v[80:81], v[12:13], off offset:176
	global_load_dwordx4 v[12:15], v119, s[56:57] offset:384
	s_waitcnt vmcnt(0)
	v_pk_mul_f32 v[12:13], v[12:13], v[24:25]
	v_pk_mul_f32 v[24:25], v[56:57], v[2:3] op_sel_hi:[1,0]
	v_cvt_pk_bf16_f32 v12, v12, v13
	v_pk_mul_f32 v[14:15], v[14:15], v[24:25]
	v_pk_mul_f32 v[24:25], v[54:55], v[2:3] op_sel_hi:[1,0]
	v_cvt_pk_bf16_f32 v13, v14, v15
	global_store_dwordx2 v[80:81], v[12:13], off offset:192
	global_load_dwordx4 v[12:15], v119, s[56:57] offset:416
	s_waitcnt vmcnt(0)
	v_pk_mul_f32 v[12:13], v[12:13], v[24:25]
	v_pk_mul_f32 v[24:25], v[52:53], v[2:3] op_sel_hi:[1,0]
	v_cvt_pk_bf16_f32 v12, v12, v13
	v_pk_mul_f32 v[14:15], v[14:15], v[24:25]
	v_pk_mul_f32 v[24:25], v[50:51], v[2:3] op_sel_hi:[1,0]
	v_cvt_pk_bf16_f32 v13, v14, v15
	global_store_dwordx2 v[80:81], v[12:13], off offset:208
	global_load_dwordx4 v[12:15], v119, s[56:57] offset:448
	s_waitcnt vmcnt(0)
	v_pk_mul_f32 v[12:13], v[12:13], v[24:25]
	v_pk_mul_f32 v[24:25], v[48:49], v[2:3] op_sel_hi:[1,0]
	v_cvt_pk_bf16_f32 v12, v12, v13
	v_pk_mul_f32 v[14:15], v[14:15], v[24:25]
	v_pk_mul_f32 v[24:25], v[44:45], v[2:3] op_sel_hi:[1,0]
	v_cvt_pk_bf16_f32 v13, v14, v15
	global_store_dwordx2 v[80:81], v[12:13], off offset:224
	global_load_dwordx4 v[12:15], v119, s[56:57] offset:480
	s_waitcnt vmcnt(0)
	v_pk_mul_f32 v[12:13], v[12:13], v[24:25]
	v_pk_mul_f32 v[24:25], v[46:47], v[2:3] op_sel_hi:[1,0]
	v_cvt_pk_bf16_f32 v12, v12, v13
	v_pk_mul_f32 v[14:15], v[14:15], v[24:25]
	s_nop 0
	v_cvt_pk_bf16_f32 v13, v14, v15
	global_store_dwordx2 v[80:81], v[12:13], off offset:240
	global_load_dword v3, v[40:41], off
	global_load_dwordx4 v[24:27], v119, s[72:73] offset:256
	global_load_dwordx4 v[28:31], v119, s[56:57] offset:512
	s_waitcnt vmcnt(2)
	v_cvt_f32_i32_e32 v3, v3
	s_waitcnt vmcnt(1)
	v_mul_f32_e32 v12, v24, v3
	v_mul_f32_e32 v13, 0.15915494, v12
	v_fma_f32 v14, v12, 0.15915494, -v13
	v_fract_f32_e32 v13, v13
	v_fmac_f32_e32 v14, 0x31dc9c88, v12
	v_add_f32_e32 v13, v13, v14
	v_pk_mul_f32 v[14:15], v[42:43], v[2:3] op_sel_hi:[1,0]
	v_sin_f32_e32 v12, v13
	s_waitcnt vmcnt(0)
; DI unsigned pk2(float a, float b) { f2_t v = {a, b}; bf2_t r = __builtin_convertvector(v, bf2_t); return __builtin_bit_cast(unsigned, r); }
; DI void q_tile(const Params& p, int mt, int hd, unsigned char* smem) {
;     ...
;     const float posf = (float)p.pos[m];
;     const float* invf = (const float*)(p.ws + WS_CTRL + 256);
; #pragma unroll
;     for (int g = 0; g < 4; ++g) {
;         float o1[4], o2[4];
; #pragma unroll
;         for (int jj = 0; jj < 4; ++jj) {
;             const int i = 8 * g + 4 * h + jj;
;             float sn, cs; sincos_rev(posf * invf[i], sn, cs);
;             const float x1 = acc[0][4][4 * g + jj] * rs * p.q_gain[128 + i], x2 = acc[0][5][4 * g + jj] * rs * p.q_gain[160 + i];
;             o1[jj] = x1 * cs - x2 * sn; o2[jj] = x2 * cs + x1 * sn;
;         }
;         u32x2 a; a.x = pk2(o1[0], o1[1]); a.y = pk2(o1[2], o1[3]);
;         u32x2 c; c.x = pk2(o2[0], o2[1]); c.y = pk2(o2[2], o2[3]);
;         *(u32x2*)(qrow + 128 + 8 * g + 4 * h) = a;
;         *(u32x2*)(qrow + 160 + 8 * g + 4 * h) = c;
;     }
	v_pk_mul_f32 v[28:29], v[28:29], v[14:15]
	v_pk_mul_f32 v[14:15], v[38:39], v[2:3] op_sel_hi:[1,0]
	global_load_dwordx4 v[38:41], v119, s[56:57] offset:640
	v_cos_f32_e32 v24, v13
	v_mul_f32_e32 v13, v25, v3
	v_pk_mul_f32 v[18:19], v[18:19], v[2:3] op_sel_hi:[1,0]
	v_pk_mul_f32 v[8:9], v[8:9], v[2:3] op_sel_hi:[1,0]
	v_pk_mul_f32 v[10:11], v[10:11], v[2:3] op_sel_hi:[1,0]
	v_pk_mul_f32 v[6:7], v[6:7], v[2:3] op_sel_hi:[1,0]
	v_pk_mul_f32 v[4:5], v[4:5], v[2:3] op_sel_hi:[1,0]
	v_pk_mul_f32 v[0:1], v[0:1], v[2:3] op_sel_hi:[1,0]
	s_waitcnt vmcnt(0)
	v_pk_mul_f32 v[38:39], v[38:39], v[14:15]
	v_mul_f32_e32 v14, 0.15915494, v13
	v_fma_f32 v15, v13, 0.15915494, -v14
	v_fract_f32_e32 v14, v14
	v_fmac_f32_e32 v15, 0x31dc9c88, v13
	v_add_f32_e32 v14, v14, v15
	v_sin_f32_e32 v13, v14
	v_cos_f32_e32 v25, v14
	v_pk_mul_f32 v[14:15], v[12:13], v[38:39]
	s_nop 0
	v_pk_fma_f32 v[14:15], v[24:25], v[28:29], v[14:15] neg_lo:[0,0,1] neg_hi:[0,0,1]
	v_pk_mul_f32 v[24:25], v[24:25], v[38:39]
	v_cvt_pk_bf16_f32 v14, v14, v15
	v_pk_fma_f32 v[12:13], v[12:13], v[28:29], v[24:25]
	v_mul_f32_e32 v24, v26, v3
	v_mul_f32_e32 v25, 0.15915494, v24
	v_fma_f32 v26, v24, 0.15915494, -v25
	v_fract_f32_e32 v25, v25
	v_fmac_f32_e32 v26, 0x31dc9c88, v24
	v_add_f32_e32 v25, v25, v26
	v_sin_f32_e32 v24, v25
	v_cos_f32_e32 v26, v25
	v_mul_f32_e32 v25, v27, v3
	v_pk_mul_f32 v[28:29], v[36:37], v[2:3] op_sel_hi:[1,0]
	v_mul_f32_e32 v27, 0.15915494, v25
	v_pk_mul_f32 v[28:29], v[30:31], v[28:29]
	v_pk_mul_f32 v[30:31], v[34:35], v[2:3] op_sel_hi:[1,0]
	v_fma_f32 v34, v25, 0.15915494, -v27
	v_fract_f32_e32 v27, v27
	v_fmac_f32_e32 v34, 0x31dc9c88, v25
	v_add_f32_e32 v27, v27, v34
	v_sin_f32_e32 v25, v27
	v_cos_f32_e32 v27, v27
	v_pk_mul_f32 v[30:31], v[40:41], v[30:31]
	v_cvt_pk_bf16_f32 v12, v12, v13
	v_pk_mul_f32 v[34:35], v[24:25], v[30:31]
	s_nop 0
	v_pk_fma_f32 v[34:35], v[26:27], v[28:29], v[34:35] neg_lo:[0,0,1] neg_hi:[0,0,1]
	v_pk_mul_f32 v[26:27], v[26:27], v[30:31]
	v_cvt_pk_bf16_f32 v15, v34, v35
	v_pk_fma_f32 v[24:25], v[24:25], v[28:29], v[26:27]
	s_nop 0
	v_cvt_pk_bf16_f32 v13, v24, v25
	global_store_dwordx2 v[80:81], v[14:15], off offset:256
	global_store_dwordx2 v[80:81], v[12:13], off offset:320
	global_load_dwordx4 v[24:27], v119, s[72:73] offset:288
	global_load_dwordx4 v[28:31], v119, s[56:57] offset:544
	s_waitcnt vmcnt(1)
	v_mul_f32_e32 v12, v24, v3
	v_mul_f32_e32 v13, 0.15915494, v12
	v_fma_f32 v14, v12, 0.15915494, -v13
	v_fract_f32_e32 v13, v13
	v_fmac_f32_e32 v14, 0x31dc9c88, v12
	v_add_f32_e32 v13, v13, v14
	v_pk_mul_f32 v[14:15], v[22:23], v[2:3] op_sel_hi:[1,0]
	v_sin_f32_e32 v12, v13
	s_waitcnt vmcnt(0)
	v_pk_mul_f32 v[28:29], v[28:29], v[14:15]
	v_pk_mul_f32 v[14:15], v[20:21], v[2:3] op_sel_hi:[1,0]
	global_load_dwordx4 v[20:23], v119, s[56:57] offset:672
	v_cos_f32_e32 v24, v13
	v_mul_f32_e32 v13, v25, v3
	s_waitcnt vmcnt(0)
	v_pk_mul_f32 v[20:21], v[20:21], v[14:15]
	v_mul_f32_e32 v14, 0.15915494, v13
	v_fma_f32 v15, v13, 0.15915494, -v14
	v_fract_f32_e32 v14, v14
	v_fmac_f32_e32 v15, 0x31dc9c88, v13
	v_add_f32_e32 v14, v14, v15
	v_sin_f32_e32 v13, v14
	v_cos_f32_e32 v25, v14
	v_pk_mul_f32 v[18:19], v[22:23], v[18:19]
	v_pk_mul_f32 v[14:15], v[12:13], v[20:21]
	v_pk_mul_f32 v[20:21], v[24:25], v[20:21]
	v_pk_fma_f32 v[14:15], v[24:25], v[28:29], v[14:15] neg_lo:[0,0,1] neg_hi:[0,0,1]
	v_pk_fma_f32 v[12:13], v[12:13], v[28:29], v[20:21]
	v_mul_f32_e32 v20, v26, v3
	v_mul_f32_e32 v21, 0.15915494, v20
	v_fma_f32 v24, v20, 0.15915494, -v21
	v_fract_f32_e32 v21, v21
	v_fmac_f32_e32 v24, 0x31dc9c88, v20
	v_add_f32_e32 v21, v21, v24
	v_sin_f32_e32 v20, v21
	v_cos_f32_e32 v24, v21
	v_mul_f32_e32 v21, v27, v3
	v_mul_f32_e32 v22, 0.15915494, v21
	v_fma_f32 v23, v21, 0.15915494, -v22
	v_fract_f32_e32 v22, v22
	v_fmac_f32_e32 v23, 0x31dc9c88, v21
	v_add_f32_e32 v22, v22, v23
	v_sin_f32_e32 v21, v22
	v_cos_f32_e32 v25, v22
	v_pk_mul_f32 v[28:29], v[32:33], v[2:3] op_sel_hi:[1,0]
	v_cvt_pk_bf16_f32 v14, v14, v15
	v_pk_mul_f32 v[28:29], v[30:31], v[28:29]
	v_pk_mul_f32 v[22:23], v[20:21], v[18:19]
	v_pk_mul_f32 v[18:19], v[24:25], v[18:19]
	v_pk_fma_f32 v[22:23], v[24:25], v[28:29], v[22:23] neg_lo:[0,0,1] neg_hi:[0,0,1]
	v_pk_fma_f32 v[18:19], v[20:21], v[28:29], v[18:19]
	v_cvt_pk_bf16_f32 v15, v22, v23
	v_cvt_pk_bf16_f32 v12, v12, v13
	v_cvt_pk_bf16_f32 v13, v18, v19
	global_store_dwordx2 v[80:81], v[14:15], off offset:272
	global_store_dwordx2 v[80:81], v[12:13], off offset:336
	global_load_dwordx4 v[12:15], v119, s[72:73] offset:320
	v_pk_mul_f32 v[20:21], v[16:17], v[2:3] op_sel_hi:[1,0]
	s_waitcnt vmcnt(0)
; DI unsigned pk2(float a, float b) { f2_t v = {a, b}; bf2_t r = __builtin_convertvector(v, bf2_t); return __builtin_bit_cast(unsigned, r); }
; DI void q_tile(const Params& p, int mt, int hd, unsigned char* smem) {
;     ...
;     for (int g = 0; g < 4; ++g) {
;         float o1[4], o2[4];
; #pragma unroll
;         for (int jj = 0; jj < 4; ++jj) {
;             const int i = 8 * g + 4 * h + jj;
;             float sn, cs; sincos_rev(posf * invf[i], sn, cs);
;             const float x1 = acc[0][4][4 * g + jj] * rs * p.q_gain[128 + i], x2 = acc[0][5][4 * g + jj] * rs * p.q_gain[160 + i];
;             o1[jj] = x1 * cs - x2 * sn; o2[jj] = x2 * cs + x1 * sn;
;         }
;         u32x2 a; a.x = pk2(o1[0], o1[1]); a.y = pk2(o1[2], o1[3]);
;         u32x2 c; c.x = pk2(o2[0], o2[1]); c.y = pk2(o2[2], o2[3]);
;         *(u32x2*)(qrow + 128 + 8 * g + 4 * h) = a;
;         *(u32x2*)(qrow + 160 + 8 * g + 4 * h) = c;
;     }
	v_mul_f32_e32 v12, v12, v3
	v_mul_f32_e32 v18, 0.15915494, v12
	v_fma_f32 v19, v12, 0.15915494, -v18
	v_fract_f32_e32 v18, v18
	v_fmac_f32_e32 v19, 0x31dc9c88, v12
	v_add_f32_e32 v12, v18, v19
	global_load_dwordx4 v[16:19], v119, s[56:57] offset:576
	v_sin_f32_e32 v24, v12
	v_cos_f32_e32 v26, v12
	v_mul_f32_e32 v12, v13, v3
	v_mul_f32_e32 v13, 0.15915494, v12
	v_mul_f32_e32 v14, v14, v3
	v_mul_f32_e32 v15, v15, v3
	s_waitcnt vmcnt(0)
	v_pk_mul_f32 v[16:17], v[16:17], v[20:21]
	global_load_dwordx4 v[20:23], v119, s[56:57] offset:704
	v_pk_mul_f32 v[10:11], v[18:19], v[10:11]
	s_waitcnt vmcnt(0)
	v_pk_mul_f32 v[8:9], v[20:21], v[8:9]
	v_fma_f32 v20, v12, 0.15915494, -v13
	v_fract_f32_e32 v13, v13
	v_fmac_f32_e32 v20, 0x31dc9c88, v12
	v_add_f32_e32 v12, v13, v20
	v_sin_f32_e32 v25, v12
	v_cos_f32_e32 v27, v12
	v_pk_mul_f32 v[6:7], v[22:23], v[6:7]
	v_pk_mul_f32 v[12:13], v[24:25], v[8:9]
	v_pk_mul_f32 v[8:9], v[26:27], v[8:9]
	v_pk_fma_f32 v[12:13], v[26:27], v[16:17], v[12:13] neg_lo:[0,0,1] neg_hi:[0,0,1]
	v_pk_fma_f32 v[8:9], v[24:25], v[16:17], v[8:9]
	v_mul_f32_e32 v16, 0.15915494, v14
	v_fma_f32 v17, v14, 0.15915494, -v16
	v_fract_f32_e32 v16, v16
	v_fmac_f32_e32 v17, 0x31dc9c88, v14
	v_add_f32_e32 v16, v16, v17
	v_mul_f32_e32 v17, 0.15915494, v15
	v_fma_f32 v18, v15, 0.15915494, -v17
	v_fract_f32_e32 v17, v17
	v_fmac_f32_e32 v18, 0x31dc9c88, v15
	v_add_f32_e32 v17, v17, v18
	v_sin_f32_e32 v14, v16
	v_sin_f32_e32 v15, v17
	v_cos_f32_e32 v16, v16
	v_cos_f32_e32 v17, v17
	v_cvt_pk_bf16_f32 v8, v8, v9
	v_pk_mul_f32 v[18:19], v[14:15], v[6:7]
	v_pk_mul_f32 v[6:7], v[16:17], v[6:7]
	v_pk_fma_f32 v[18:19], v[16:17], v[10:11], v[18:19] neg_lo:[0,0,1] neg_hi:[0,0,1]
	v_pk_fma_f32 v[6:7], v[14:15], v[10:11], v[6:7]
	v_cvt_pk_bf16_f32 v10, v12, v13
	v_cvt_pk_bf16_f32 v11, v18, v19
	v_cvt_pk_bf16_f32 v9, v6, v7
	global_store_dwordx2 v[80:81], v[10:11], off offset:288
	global_store_dwordx2 v[80:81], v[8:9], off offset:352
	global_load_dwordx4 v[6:9], v119, s[72:73] offset:352
	s_waitcnt vmcnt(0)
	v_mul_f32_e32 v6, v6, v3
	v_mul_f32_e32 v10, 0.15915494, v6
	v_fma_f32 v11, v6, 0.15915494, -v10
	v_fract_f32_e32 v10, v10
	v_fmac_f32_e32 v11, 0x31dc9c88, v6
	v_add_f32_e32 v6, v10, v11
	global_load_dwordx4 v[10:13], v119, s[56:57] offset:608
	global_load_dwordx4 v[14:17], v119, s[56:57] offset:736
	v_sin_f32_e32 v18, v6
	v_cos_f32_e32 v20, v6
	v_mul_f32_e32 v6, v7, v3
	v_mul_f32_e32 v7, 0.15915494, v6
	v_mul_f32_e32 v8, v8, v3
	s_waitcnt vmcnt(1)
	v_pk_mul_f32 v[4:5], v[10:11], v[4:5]
	v_pk_mul_f32 v[10:11], v[98:99], v[2:3] op_sel_hi:[1,0]
	v_pk_mul_f32 v[0:1], v[12:13], v[0:1]
	s_waitcnt vmcnt(0)
	v_pk_mul_f32 v[10:11], v[14:15], v[10:11]
	v_fma_f32 v14, v6, 0.15915494, -v7
	v_fract_f32_e32 v7, v7
	v_fmac_f32_e32 v14, 0x31dc9c88, v6
	v_add_f32_e32 v6, v7, v14
	v_sin_f32_e32 v19, v6
	v_cos_f32_e32 v21, v6
	v_pk_mul_f32 v[12:13], v[96:97], v[2:3] op_sel_hi:[1,0]
	v_mul_f32_e32 v2, v9, v3
	v_pk_mul_f32 v[6:7], v[18:19], v[10:11]
	v_pk_mul_f32 v[10:11], v[20:21], v[10:11]
	v_pk_fma_f32 v[6:7], v[20:21], v[4:5], v[6:7] neg_lo:[0,0,1] neg_hi:[0,0,1]
	v_pk_fma_f32 v[4:5], v[18:19], v[4:5], v[10:11]
	v_mul_f32_e32 v10, 0.15915494, v8
	v_mul_f32_e32 v3, 0.15915494, v2
	v_fma_f32 v11, v8, 0.15915494, -v10
	v_fma_f32 v9, v2, 0.15915494, -v3
	v_fract_f32_e32 v10, v10
	v_fmac_f32_e32 v11, 0x31dc9c88, v8
	v_fract_f32_e32 v3, v3
	v_fmac_f32_e32 v9, 0x31dc9c88, v2
	v_add_f32_e32 v10, v10, v11
	v_add_f32_e32 v2, v3, v9
	v_sin_f32_e32 v8, v10
	v_sin_f32_e32 v9, v2
	v_cos_f32_e32 v10, v10
	v_cos_f32_e32 v11, v2
	v_pk_mul_f32 v[12:13], v[16:17], v[12:13]
	v_cvt_pk_bf16_f32 v6, v6, v7
	v_pk_mul_f32 v[2:3], v[8:9], v[12:13]
	s_nop 0
	v_pk_fma_f32 v[2:3], v[10:11], v[0:1], v[2:3] neg_lo:[0,0,1] neg_hi:[0,0,1]
	v_pk_mul_f32 v[10:11], v[10:11], v[12:13]
	v_cvt_pk_bf16_f32 v7, v2, v3
	v_pk_fma_f32 v[0:1], v[8:9], v[0:1], v[10:11]
	v_cvt_pk_bf16_f32 v2, v4, v5
	v_cvt_pk_bf16_f32 v3, v0, v1
	global_store_dwordx2 v[80:81], v[6:7], off offset:304
	global_store_dwordx2 v[80:81], v[2:3], off offset:368
